# S5 pre-phase Kt table via f32 MFMA 16x16x4 (was scalar f32 VALU loop); out-phase epilogues staged through LDS with 16-byte accesses; 4-deep K-fragment read pipeline in attention QK
# speedup vs baseline: 1.0735x; 1.0164x over previous
.LBB0_262:
	s_add_i32 s58, s58, s82
	s_add_i32 s57, s57, s82
	v_and_b32_e32 v231, 15, v181
	v_bfe_u32 v135, v181, 4, 2
	v_lshlrev_b32_e32 v230, 4, v231
	s_movk_i32 s20, 0x110
	v_mad_u32_u24 v230, v135, s20, v230
	v_lshlrev_b32_e32 v180, 2, v231
	s_movk_i32 s20, 0x440
	v_mad_u32_u24 v180, v135, s20, v180
	v_lshlrev_b32_e32 v135, 12, v135
	v_lshl_add_u32 v135, v231, 4, v135
	v_lshrrev_b32_e32 v231, 6, v181
	v_mul_u32_u24_e32 v231, 0x4400, v231
	v_add_u32_e32 v230, v230, v231
	v_add_u32_e32 v180, v180, v231
	v_bfe_u32 v231, v181, 6, 2
	v_lshl_add_u32 v135, v231, 8, v135
	v_lshrrev_b32_e32 v231, 8, v181
	v_lshl_add_u32 v135, v231, 19, v135
	s_lshl_b32 s20, s48, 20
	v_add_u32_e32 v135, s20, v135
	s_lshl_b32 s20, s6, 10
	v_add_u32_e32 v135, s20, v135
	s_mov_b32 s50, s36
	s_mov_b32 s51, s37
	s_mov_b32 s52, s78
	s_mov_b32 s53, s79
	global_load_dwordx4 v[130:133], v135, s[50:51]
	s_add_u32 s50, s50, 0x4000
	s_addc_u32 s51, s51, 0
	global_load_dwordx4 v[136:139], v135, s[50:51]
	s_add_u32 s50, s50, 0x4000
	s_addc_u32 s51, s51, 0
	global_load_dwordx4 v[140:143], v135, s[50:51]
	s_add_u32 s50, s50, 0x4000
	s_addc_u32 s51, s51, 0
	global_load_dwordx4 v[144:147], v135, s[50:51]
	s_add_u32 s50, s50, 0x4000
	s_addc_u32 s51, s51, 0
	global_load_dwordx4 v[148:151], v135, s[50:51]
	s_add_u32 s50, s50, 0x4000
	s_addc_u32 s51, s51, 0
	global_load_dwordx4 v[152:155], v135, s[50:51]
	s_add_u32 s50, s50, 0x4000
	s_addc_u32 s51, s51, 0
	global_load_dwordx4 v[156:159], v135, s[50:51]
	s_add_u32 s50, s50, 0x4000
	s_addc_u32 s51, s51, 0
	global_load_dwordx4 v[160:163], v135, s[50:51]
	s_add_u32 s50, s50, 0x4000
	s_addc_u32 s51, s51, 0
	global_load_dwordx4 v[164:167], v135, s[50:51]
	s_add_u32 s50, s50, 0x4000
	s_addc_u32 s51, s51, 0
	global_load_dwordx4 v[168:171], v135, s[50:51]
	s_add_u32 s50, s50, 0x4000
	s_addc_u32 s51, s51, 0
	global_load_dwordx4 v[172:175], v135, s[50:51]
	s_add_u32 s50, s50, 0x4000
	s_addc_u32 s51, s51, 0
	global_load_dwordx4 v[176:179], v135, s[50:51]
	s_add_u32 s50, s50, 0x4000
	s_addc_u32 s51, s51, 0
	global_load_dwordx4 v[182:185], v135, s[50:51]
	s_add_u32 s50, s50, 0x4000
	s_addc_u32 s51, s51, 0
	global_load_dwordx4 v[186:189], v135, s[50:51]
	s_add_u32 s50, s50, 0x4000
	s_addc_u32 s51, s51, 0
	global_load_dwordx4 v[190:193], v135, s[50:51]
	s_add_u32 s50, s50, 0x4000
	s_addc_u32 s51, s51, 0
	global_load_dwordx4 v[194:197], v135, s[50:51]
	s_add_u32 s50, s50, 0x4000
	s_addc_u32 s51, s51, 0
	ds_write_b32 v180, v124
	ds_write_b32 v180, v125 offset:272
	ds_write_b32 v180, v126 offset:544
	ds_write_b32 v180, v127 offset:816
	ds_write_b32 v180, v120 offset:64
	ds_write_b32 v180, v121 offset:336
	ds_write_b32 v180, v122 offset:608
	ds_write_b32 v180, v123 offset:880
	ds_write_b32 v180, v116 offset:128
	ds_write_b32 v180, v117 offset:400
	ds_write_b32 v180, v118 offset:672
	ds_write_b32 v180, v119 offset:944
	ds_write_b32 v180, v112 offset:192
	ds_write_b32 v180, v113 offset:464
	ds_write_b32 v180, v114 offset:736
	ds_write_b32 v180, v115 offset:1008
	ds_write_b32 v180, v108 offset:4352
	ds_write_b32 v180, v109 offset:4624
	ds_write_b32 v180, v110 offset:4896
	ds_write_b32 v180, v111 offset:5168
	ds_write_b32 v180, v104 offset:4416
	ds_write_b32 v180, v105 offset:4688
	ds_write_b32 v180, v106 offset:4960
	ds_write_b32 v180, v107 offset:5232
	ds_write_b32 v180, v100 offset:4480
	ds_write_b32 v180, v101 offset:4752
	ds_write_b32 v180, v102 offset:5024
	ds_write_b32 v180, v103 offset:5296
	ds_write_b32 v180, v96 offset:4544
	ds_write_b32 v180, v97 offset:4816
	ds_write_b32 v180, v98 offset:5088
	ds_write_b32 v180, v99 offset:5360
	ds_write_b32 v180, v92 offset:8704
	ds_write_b32 v180, v93 offset:8976
	ds_write_b32 v180, v94 offset:9248
	ds_write_b32 v180, v95 offset:9520
	ds_write_b32 v180, v88 offset:8768
	ds_write_b32 v180, v89 offset:9040
	ds_write_b32 v180, v90 offset:9312
	ds_write_b32 v180, v91 offset:9584
	ds_write_b32 v180, v84 offset:8832
	ds_write_b32 v180, v85 offset:9104
	ds_write_b32 v180, v86 offset:9376
	ds_write_b32 v180, v87 offset:9648
	ds_write_b32 v180, v80 offset:8896
	ds_write_b32 v180, v81 offset:9168
	ds_write_b32 v180, v82 offset:9440
	ds_write_b32 v180, v83 offset:9712
	ds_write_b32 v180, v76 offset:13056
	ds_write_b32 v180, v77 offset:13328
	ds_write_b32 v180, v78 offset:13600
	ds_write_b32 v180, v79 offset:13872
	ds_write_b32 v180, v72 offset:13120
	ds_write_b32 v180, v73 offset:13392
	ds_write_b32 v180, v74 offset:13664
	ds_write_b32 v180, v75 offset:13936
	ds_write_b32 v180, v68 offset:13184
	ds_write_b32 v180, v69 offset:13456
	ds_write_b32 v180, v70 offset:13728
	ds_write_b32 v180, v71 offset:14000
	ds_write_b32 v180, v64 offset:13248
	ds_write_b32 v180, v65 offset:13520
	ds_write_b32 v180, v66 offset:13792
	ds_write_b32 v180, v67 offset:14064
	s_waitcnt lgkmcnt(0)
	ds_read_b128 v[198:201], v230
	ds_read_b128 v[202:205], v230 offset:1088
	ds_read_b128 v[206:209], v230 offset:2176
	ds_read_b128 v[210:213], v230 offset:3264
	ds_read_b128 v[214:217], v230 offset:4352
	ds_read_b128 v[218:221], v230 offset:5440
	ds_read_b128 v[222:225], v230 offset:6528
	ds_read_b128 v[226:229], v230 offset:7616
	s_waitcnt vmcnt(15) lgkmcnt(7)
	v_pk_add_f32 v[130:131], v[130:131], v[198:199]
	v_pk_add_f32 v[132:133], v[132:133], v[200:201]
	global_store_dwordx4 v135, v[130:133], s[52:53] sc1
	s_add_u32 s52, s52, 0x4000
	s_addc_u32 s53, s53, 0
	s_waitcnt vmcnt(15) lgkmcnt(6)
	v_pk_add_f32 v[136:137], v[136:137], v[202:203]
	v_pk_add_f32 v[138:139], v[138:139], v[204:205]
	global_store_dwordx4 v135, v[136:139], s[52:53] sc1
	s_add_u32 s52, s52, 0x4000
	s_addc_u32 s53, s53, 0
	s_waitcnt vmcnt(15) lgkmcnt(5)
	v_pk_add_f32 v[140:141], v[140:141], v[206:207]
	v_pk_add_f32 v[142:143], v[142:143], v[208:209]
	global_store_dwordx4 v135, v[140:143], s[52:53] sc1
	s_add_u32 s52, s52, 0x4000
	s_addc_u32 s53, s53, 0
	s_waitcnt vmcnt(15) lgkmcnt(4)
	v_pk_add_f32 v[144:145], v[144:145], v[210:211]
	v_pk_add_f32 v[146:147], v[146:147], v[212:213]
	global_store_dwordx4 v135, v[144:147], s[52:53] sc1
	s_add_u32 s52, s52, 0x4000
	s_addc_u32 s53, s53, 0
	s_waitcnt vmcnt(15) lgkmcnt(3)
	v_pk_add_f32 v[148:149], v[148:149], v[214:215]
	v_pk_add_f32 v[150:151], v[150:151], v[216:217]
	global_store_dwordx4 v135, v[148:151], s[52:53] sc1
	s_add_u32 s52, s52, 0x4000
	s_addc_u32 s53, s53, 0
	s_waitcnt vmcnt(15) lgkmcnt(2)
	v_pk_add_f32 v[152:153], v[152:153], v[218:219]
	v_pk_add_f32 v[154:155], v[154:155], v[220:221]
	global_store_dwordx4 v135, v[152:155], s[52:53] sc1
	s_add_u32 s52, s52, 0x4000
	s_addc_u32 s53, s53, 0
	s_waitcnt vmcnt(15) lgkmcnt(1)
	v_pk_add_f32 v[156:157], v[156:157], v[222:223]
	v_pk_add_f32 v[158:159], v[158:159], v[224:225]
	global_store_dwordx4 v135, v[156:159], s[52:53] sc1
	s_add_u32 s52, s52, 0x4000
	s_addc_u32 s53, s53, 0
	s_waitcnt vmcnt(15) lgkmcnt(0)
	v_pk_add_f32 v[160:161], v[160:161], v[226:227]
	v_pk_add_f32 v[162:163], v[162:163], v[228:229]
	global_store_dwordx4 v135, v[160:163], s[52:53] sc1
	s_add_u32 s52, s52, 0x4000
	s_addc_u32 s53, s53, 0
	global_load_dwordx4 v[130:133], v135, s[50:51]
	s_add_u32 s50, s50, 0x4000
	s_addc_u32 s51, s51, 0
	global_load_dwordx4 v[136:139], v135, s[50:51]
	s_add_u32 s50, s50, 0x4000
	s_addc_u32 s51, s51, 0
	global_load_dwordx4 v[140:143], v135, s[50:51]
	s_add_u32 s50, s50, 0x4000
	s_addc_u32 s51, s51, 0
	global_load_dwordx4 v[144:147], v135, s[50:51]
	s_add_u32 s50, s50, 0x4000
	s_addc_u32 s51, s51, 0
	global_load_dwordx4 v[148:151], v135, s[50:51]
	s_add_u32 s50, s50, 0x4000
	s_addc_u32 s51, s51, 0
	global_load_dwordx4 v[152:155], v135, s[50:51]
	s_add_u32 s50, s50, 0x4000
	s_addc_u32 s51, s51, 0
	global_load_dwordx4 v[156:159], v135, s[50:51]
	s_add_u32 s50, s50, 0x4000
	s_addc_u32 s51, s51, 0
	global_load_dwordx4 v[160:163], v135, s[50:51]
	s_add_u32 s50, s50, 0x4000
	s_addc_u32 s51, s51, 0
	ds_read_b128 v[198:201], v230 offset:8704
	ds_read_b128 v[202:205], v230 offset:9792
	ds_read_b128 v[206:209], v230 offset:10880
	ds_read_b128 v[210:213], v230 offset:11968
	ds_read_b128 v[214:217], v230 offset:13056
	ds_read_b128 v[218:221], v230 offset:14144
	ds_read_b128 v[222:225], v230 offset:15232
	ds_read_b128 v[226:229], v230 offset:16320
	s_waitcnt vmcnt(15) lgkmcnt(7)
	v_pk_add_f32 v[164:165], v[164:165], v[198:199]
	v_pk_add_f32 v[166:167], v[166:167], v[200:201]
	global_store_dwordx4 v135, v[164:167], s[52:53] sc1
	s_add_u32 s52, s52, 0x4000
	s_addc_u32 s53, s53, 0
	s_waitcnt vmcnt(15) lgkmcnt(6)
	v_pk_add_f32 v[168:169], v[168:169], v[202:203]
	v_pk_add_f32 v[170:171], v[170:171], v[204:205]
	global_store_dwordx4 v135, v[168:171], s[52:53] sc1
	s_add_u32 s52, s52, 0x4000
	s_addc_u32 s53, s53, 0
	s_waitcnt vmcnt(15) lgkmcnt(5)
	v_pk_add_f32 v[172:173], v[172:173], v[206:207]
	v_pk_add_f32 v[174:175], v[174:175], v[208:209]
	global_store_dwordx4 v135, v[172:175], s[52:53] sc1
	s_add_u32 s52, s52, 0x4000
	s_addc_u32 s53, s53, 0
	s_waitcnt vmcnt(15) lgkmcnt(4)
	v_pk_add_f32 v[176:177], v[176:177], v[210:211]
	v_pk_add_f32 v[178:179], v[178:179], v[212:213]
	global_store_dwordx4 v135, v[176:179], s[52:53] sc1
	s_add_u32 s52, s52, 0x4000
	s_addc_u32 s53, s53, 0
	s_waitcnt vmcnt(15) lgkmcnt(3)
	v_pk_add_f32 v[182:183], v[182:183], v[214:215]
	v_pk_add_f32 v[184:185], v[184:185], v[216:217]
	global_store_dwordx4 v135, v[182:185], s[52:53] sc1
	s_add_u32 s52, s52, 0x4000
	s_addc_u32 s53, s53, 0
	s_waitcnt vmcnt(15) lgkmcnt(2)
	v_pk_add_f32 v[186:187], v[186:187], v[218:219]
	v_pk_add_f32 v[188:189], v[188:189], v[220:221]
	global_store_dwordx4 v135, v[186:189], s[52:53] sc1
	s_add_u32 s52, s52, 0x4000
	s_addc_u32 s53, s53, 0
	s_waitcnt vmcnt(15) lgkmcnt(1)
	v_pk_add_f32 v[190:191], v[190:191], v[222:223]
	v_pk_add_f32 v[192:193], v[192:193], v[224:225]
	global_store_dwordx4 v135, v[190:193], s[52:53] sc1
	s_add_u32 s52, s52, 0x4000
	s_addc_u32 s53, s53, 0
	s_waitcnt vmcnt(15) lgkmcnt(0)
	v_pk_add_f32 v[194:195], v[194:195], v[226:227]
	v_pk_add_f32 v[196:197], v[196:197], v[228:229]
	global_store_dwordx4 v135, v[194:197], s[52:53] sc1
	s_add_u32 s52, s52, 0x4000
	s_addc_u32 s53, s53, 0
	s_waitcnt lgkmcnt(0)
	global_load_dwordx4 v[164:167], v135, s[50:51]
	s_add_u32 s50, s50, 0x4000
	s_addc_u32 s51, s51, 0
	global_load_dwordx4 v[168:171], v135, s[50:51]
	s_add_u32 s50, s50, 0x4000
	s_addc_u32 s51, s51, 0
	global_load_dwordx4 v[172:175], v135, s[50:51]
	s_add_u32 s50, s50, 0x4000
	s_addc_u32 s51, s51, 0
	global_load_dwordx4 v[176:179], v135, s[50:51]
	s_add_u32 s50, s50, 0x4000
	s_addc_u32 s51, s51, 0
	global_load_dwordx4 v[182:185], v135, s[50:51]
	s_add_u32 s50, s50, 0x4000
	s_addc_u32 s51, s51, 0
	global_load_dwordx4 v[186:189], v135, s[50:51]
	s_add_u32 s50, s50, 0x4000
	s_addc_u32 s51, s51, 0
	global_load_dwordx4 v[190:193], v135, s[50:51]
	s_add_u32 s50, s50, 0x4000
	s_addc_u32 s51, s51, 0
	global_load_dwordx4 v[194:197], v135, s[50:51]
	s_add_u32 s50, s50, 0x4000
	s_addc_u32 s51, s51, 0
	ds_write_b32 v180, v60
	ds_write_b32 v180, v61 offset:272
	ds_write_b32 v180, v62 offset:544
	ds_write_b32 v180, v63 offset:816
	ds_write_b32 v180, v56 offset:64
	ds_write_b32 v180, v57 offset:336
	ds_write_b32 v180, v58 offset:608
	ds_write_b32 v180, v59 offset:880
	ds_write_b32 v180, v52 offset:128
	ds_write_b32 v180, v53 offset:400
	ds_write_b32 v180, v54 offset:672
	ds_write_b32 v180, v55 offset:944
	ds_write_b32 v180, v48 offset:192
	ds_write_b32 v180, v49 offset:464
	ds_write_b32 v180, v50 offset:736
	ds_write_b32 v180, v51 offset:1008
	ds_write_b32 v180, v44 offset:4352
	ds_write_b32 v180, v45 offset:4624
	ds_write_b32 v180, v46 offset:4896
	ds_write_b32 v180, v47 offset:5168
	ds_write_b32 v180, v40 offset:4416
	ds_write_b32 v180, v41 offset:4688
	ds_write_b32 v180, v42 offset:4960
	ds_write_b32 v180, v43 offset:5232
	ds_write_b32 v180, v36 offset:4480
	ds_write_b32 v180, v37 offset:4752
	ds_write_b32 v180, v38 offset:5024
	ds_write_b32 v180, v39 offset:5296
	ds_write_b32 v180, v32 offset:4544
	ds_write_b32 v180, v33 offset:4816
	ds_write_b32 v180, v34 offset:5088
	ds_write_b32 v180, v35 offset:5360
	ds_write_b32 v180, v28 offset:8704
	ds_write_b32 v180, v29 offset:8976
	ds_write_b32 v180, v30 offset:9248
	ds_write_b32 v180, v31 offset:9520
	ds_write_b32 v180, v20 offset:8768
	ds_write_b32 v180, v21 offset:9040
	ds_write_b32 v180, v22 offset:9312
	ds_write_b32 v180, v23 offset:9584
	ds_write_b32 v180, v16 offset:8832
	ds_write_b32 v180, v17 offset:9104
	ds_write_b32 v180, v18 offset:9376
	ds_write_b32 v180, v19 offset:9648
	ds_write_b32 v180, v8 offset:8896
	ds_write_b32 v180, v9 offset:9168
	ds_write_b32 v180, v10 offset:9440
	ds_write_b32 v180, v11 offset:9712
	ds_write_b32 v180, v4 offset:13056
	ds_write_b32 v180, v5 offset:13328
	ds_write_b32 v180, v6 offset:13600
	ds_write_b32 v180, v7 offset:13872
	ds_write_b32 v180, v0 offset:13120
	ds_write_b32 v180, v1 offset:13392
	ds_write_b32 v180, v2 offset:13664
	ds_write_b32 v180, v3 offset:13936
	ds_write_b32 v180, v24 offset:13184
	ds_write_b32 v180, v25 offset:13456
	ds_write_b32 v180, v26 offset:13728
	ds_write_b32 v180, v27 offset:14000
	ds_write_b32 v180, v12 offset:13248
	ds_write_b32 v180, v13 offset:13520
	ds_write_b32 v180, v14 offset:13792
	ds_write_b32 v180, v15 offset:14064
	s_waitcnt lgkmcnt(0)
	ds_read_b128 v[198:201], v230
	ds_read_b128 v[202:205], v230 offset:1088
	ds_read_b128 v[206:209], v230 offset:2176
	ds_read_b128 v[210:213], v230 offset:3264
	ds_read_b128 v[214:217], v230 offset:4352
	ds_read_b128 v[218:221], v230 offset:5440
	ds_read_b128 v[222:225], v230 offset:6528
	ds_read_b128 v[226:229], v230 offset:7616
	s_waitcnt vmcnt(15) lgkmcnt(7)
	v_pk_add_f32 v[130:131], v[130:131], v[198:199]
	v_pk_add_f32 v[132:133], v[132:133], v[200:201]
	global_store_dwordx4 v135, v[130:133], s[52:53] sc1
	s_add_u32 s52, s52, 0x4000
	s_addc_u32 s53, s53, 0
	s_waitcnt vmcnt(15) lgkmcnt(6)
	v_pk_add_f32 v[136:137], v[136:137], v[202:203]
	v_pk_add_f32 v[138:139], v[138:139], v[204:205]
	global_store_dwordx4 v135, v[136:139], s[52:53] sc1
	s_add_u32 s52, s52, 0x4000
	s_addc_u32 s53, s53, 0
	s_waitcnt vmcnt(15) lgkmcnt(5)
	v_pk_add_f32 v[140:141], v[140:141], v[206:207]
	v_pk_add_f32 v[142:143], v[142:143], v[208:209]
	global_store_dwordx4 v135, v[140:143], s[52:53] sc1
	s_add_u32 s52, s52, 0x4000
	s_addc_u32 s53, s53, 0
	s_waitcnt vmcnt(15) lgkmcnt(4)
	v_pk_add_f32 v[144:145], v[144:145], v[210:211]
	v_pk_add_f32 v[146:147], v[146:147], v[212:213]
	global_store_dwordx4 v135, v[144:147], s[52:53] sc1
	s_add_u32 s52, s52, 0x4000
	s_addc_u32 s53, s53, 0
	s_waitcnt vmcnt(15) lgkmcnt(3)
	v_pk_add_f32 v[148:149], v[148:149], v[214:215]
	v_pk_add_f32 v[150:151], v[150:151], v[216:217]
	global_store_dwordx4 v135, v[148:151], s[52:53] sc1
	s_add_u32 s52, s52, 0x4000
	s_addc_u32 s53, s53, 0
	s_waitcnt vmcnt(15) lgkmcnt(2)
	v_pk_add_f32 v[152:153], v[152:153], v[218:219]
	v_pk_add_f32 v[154:155], v[154:155], v[220:221]
	global_store_dwordx4 v135, v[152:155], s[52:53] sc1
	s_add_u32 s52, s52, 0x4000
	s_addc_u32 s53, s53, 0
	s_waitcnt vmcnt(15) lgkmcnt(1)
	v_pk_add_f32 v[156:157], v[156:157], v[222:223]
	v_pk_add_f32 v[158:159], v[158:159], v[224:225]
	global_store_dwordx4 v135, v[156:159], s[52:53] sc1
	s_add_u32 s52, s52, 0x4000
	s_addc_u32 s53, s53, 0
	s_waitcnt vmcnt(15) lgkmcnt(0)
	v_pk_add_f32 v[160:161], v[160:161], v[226:227]
	v_pk_add_f32 v[162:163], v[162:163], v[228:229]
	global_store_dwordx4 v135, v[160:163], s[52:53] sc1
	s_add_u32 s52, s52, 0x4000
	s_addc_u32 s53, s53, 0
	ds_read_b128 v[198:201], v230 offset:8704
	ds_read_b128 v[202:205], v230 offset:9792
	ds_read_b128 v[206:209], v230 offset:10880
	ds_read_b128 v[210:213], v230 offset:11968
	ds_read_b128 v[214:217], v230 offset:13056
	ds_read_b128 v[218:221], v230 offset:14144
	ds_read_b128 v[222:225], v230 offset:15232
	ds_read_b128 v[226:229], v230 offset:16320
	s_waitcnt vmcnt(7) lgkmcnt(7)
	v_pk_add_f32 v[164:165], v[164:165], v[198:199]
	v_pk_add_f32 v[166:167], v[166:167], v[200:201]
	global_store_dwordx4 v135, v[164:167], s[52:53] sc1
	s_add_u32 s52, s52, 0x4000
	s_addc_u32 s53, s53, 0
	s_waitcnt vmcnt(7) lgkmcnt(6)
	v_pk_add_f32 v[168:169], v[168:169], v[202:203]
	v_pk_add_f32 v[170:171], v[170:171], v[204:205]
	global_store_dwordx4 v135, v[168:171], s[52:53] sc1
	s_add_u32 s52, s52, 0x4000
	s_addc_u32 s53, s53, 0
	s_waitcnt vmcnt(7) lgkmcnt(5)
	v_pk_add_f32 v[172:173], v[172:173], v[206:207]
	v_pk_add_f32 v[174:175], v[174:175], v[208:209]
	global_store_dwordx4 v135, v[172:175], s[52:53] sc1
	s_add_u32 s52, s52, 0x4000
	s_addc_u32 s53, s53, 0
	s_waitcnt vmcnt(7) lgkmcnt(4)
	v_pk_add_f32 v[176:177], v[176:177], v[210:211]
	v_pk_add_f32 v[178:179], v[178:179], v[212:213]
	global_store_dwordx4 v135, v[176:179], s[52:53] sc1
	s_add_u32 s52, s52, 0x4000
	s_addc_u32 s53, s53, 0
	s_waitcnt vmcnt(7) lgkmcnt(3)
	v_pk_add_f32 v[182:183], v[182:183], v[214:215]
	v_pk_add_f32 v[184:185], v[184:185], v[216:217]
	global_store_dwordx4 v135, v[182:185], s[52:53] sc1
	s_add_u32 s52, s52, 0x4000
	s_addc_u32 s53, s53, 0
	s_waitcnt vmcnt(7) lgkmcnt(2)
	v_pk_add_f32 v[186:187], v[186:187], v[218:219]
	v_pk_add_f32 v[188:189], v[188:189], v[220:221]
	global_store_dwordx4 v135, v[186:189], s[52:53] sc1
	s_add_u32 s52, s52, 0x4000
	s_addc_u32 s53, s53, 0
	s_waitcnt vmcnt(7) lgkmcnt(1)
	v_pk_add_f32 v[190:191], v[190:191], v[222:223]
	v_pk_add_f32 v[192:193], v[192:193], v[224:225]
	global_store_dwordx4 v135, v[190:193], s[52:53] sc1
	s_add_u32 s52, s52, 0x4000
	s_addc_u32 s53, s53, 0
	s_waitcnt vmcnt(7) lgkmcnt(0)
	v_pk_add_f32 v[194:195], v[194:195], v[226:227]
	v_pk_add_f32 v[196:197], v[196:197], v[228:229]
	global_store_dwordx4 v135, v[194:197], s[52:53] sc1
	s_add_u32 s52, s52, 0x4000
	s_addc_u32 s53, s53, 0
	s_cmpk_lt_i32 s58, 0x100
	s_cbranch_scc0 .LBB0_269

.LBB0_366:
	s_or_b64 exec, exec, s[10:11]
	s_waitcnt lgkmcnt(0)
	s_barrier
	v_and_b32_e32 v100, 15, v181
	v_bfe_u32 v101, v181, 4, 2
	v_lshrrev_b32_e32 v108, 6, v181
	v_lshl_add_u32 v102, v100, 6, v101
	v_lshlrev_b32_e32 v102, 2, v102
	v_add_u32_e32 v102, 0x4200, v102
	v_lshlrev_b32_e32 v103, 2, v101
	v_lshl_add_u32 v104, v101, 4, v100
	v_lshlrev_b32_e32 v104, 2, v104
	v_add_u32_e32 v104, 0x2200, v104
	v_lshl_add_u32 v105, v101, 6, v100
	v_lshlrev_b32_e32 v105, 2, v105
	v_add_u32_e32 v105, 0x6400, v105
	v_readfirstlane_b32 s10, v108
	s_lshl_b32 s37, s36, 4
.Lkt_tau:
	s_lshl_b32 s11, s10, 8
	v_add_u32_e32 v106, s11, v103
	v_mov_b32_e32 v112, 0
	v_mov_b32_e32 v113, 0
	v_mov_b32_e32 v114, 0
	v_mov_b32_e32 v115, 0
	ds_read_b32 v116, v102
	ds_read_b32 v117, v102 offset:4096
	ds_read_b32 v118, v106
	ds_read_b32 v119, v106 offset:4352
	ds_read_b32 v120, v104
	ds_read_b32 v121, v104 offset:4096
	ds_read_b32 v122, v102 offset:16
	ds_read_b32 v123, v102 offset:4112
	ds_read_b32 v124, v106 offset:16
	ds_read_b32 v125, v106 offset:4368
	ds_read_b32 v126, v104 offset:256
	ds_read_b32 v127, v104 offset:4352
	s_waitcnt lgkmcnt(6)
	v_mul_f32_e32 v108, v117, v119
	v_mul_f32_e32 v107, v116, v119
	v_fma_f32 v116, v116, v118, -v108
	v_fma_f32 v117, -v117, v118, -v107
	s_nop 1
	v_mfma_f32_16x16x4_f32 v[112:115], v116, v120, v[112:115]
	v_mfma_f32_16x16x4_f32 v[112:115], v117, v121, v[112:115]
	s_waitcnt lgkmcnt(0)
	v_mul_f32_e32 v108, v123, v125
	v_mul_f32_e32 v107, v122, v125
	v_fma_f32 v122, v122, v124, -v108
	v_fma_f32 v123, -v123, v124, -v107
	s_nop 1
	v_mfma_f32_16x16x4_f32 v[112:115], v122, v126, v[112:115]
	v_mfma_f32_16x16x4_f32 v[112:115], v123, v127, v[112:115]
	ds_read_b32 v116, v102 offset:32
	ds_read_b32 v117, v102 offset:4128
	ds_read_b32 v118, v106 offset:32
	ds_read_b32 v119, v106 offset:4384
	ds_read_b32 v120, v104 offset:512
	ds_read_b32 v121, v104 offset:4608
	ds_read_b32 v122, v102 offset:48
	ds_read_b32 v123, v102 offset:4144
	ds_read_b32 v124, v106 offset:48
	ds_read_b32 v125, v106 offset:4400
	ds_read_b32 v126, v104 offset:768
	ds_read_b32 v127, v104 offset:4864
	s_waitcnt lgkmcnt(6)
	v_mul_f32_e32 v108, v117, v119
	v_mul_f32_e32 v107, v116, v119
	v_fma_f32 v116, v116, v118, -v108
	v_fma_f32 v117, -v117, v118, -v107
	s_nop 1
	v_mfma_f32_16x16x4_f32 v[112:115], v116, v120, v[112:115]
	v_mfma_f32_16x16x4_f32 v[112:115], v117, v121, v[112:115]
	s_waitcnt lgkmcnt(0)
	v_mul_f32_e32 v108, v123, v125
	v_mul_f32_e32 v107, v122, v125
	v_fma_f32 v122, v122, v124, -v108
	v_fma_f32 v123, -v123, v124, -v107
	s_nop 1
	v_mfma_f32_16x16x4_f32 v[112:115], v122, v126, v[112:115]
	v_mfma_f32_16x16x4_f32 v[112:115], v123, v127, v[112:115]
	ds_read_b32 v116, v102 offset:64
	ds_read_b32 v117, v102 offset:4160
	ds_read_b32 v118, v106 offset:64
	ds_read_b32 v119, v106 offset:4416
	ds_read_b32 v120, v104 offset:1024
	ds_read_b32 v121, v104 offset:5120
	ds_read_b32 v122, v102 offset:80
	ds_read_b32 v123, v102 offset:4176
	ds_read_b32 v124, v106 offset:80
	ds_read_b32 v125, v106 offset:4432
	ds_read_b32 v126, v104 offset:1280
	ds_read_b32 v127, v104 offset:5376
	s_waitcnt lgkmcnt(6)
	v_mul_f32_e32 v108, v117, v119
	v_mul_f32_e32 v107, v116, v119
	v_fma_f32 v116, v116, v118, -v108
	v_fma_f32 v117, -v117, v118, -v107
	s_nop 1
	v_mfma_f32_16x16x4_f32 v[112:115], v116, v120, v[112:115]
	v_mfma_f32_16x16x4_f32 v[112:115], v117, v121, v[112:115]
	s_waitcnt lgkmcnt(0)
	v_mul_f32_e32 v108, v123, v125
	v_mul_f32_e32 v107, v122, v125
	v_fma_f32 v122, v122, v124, -v108
	v_fma_f32 v123, -v123, v124, -v107
	s_nop 1
	v_mfma_f32_16x16x4_f32 v[112:115], v122, v126, v[112:115]
	v_mfma_f32_16x16x4_f32 v[112:115], v123, v127, v[112:115]
	ds_read_b32 v116, v102 offset:96
	ds_read_b32 v117, v102 offset:4192
	ds_read_b32 v118, v106 offset:96
	ds_read_b32 v119, v106 offset:4448
	ds_read_b32 v120, v104 offset:1536
	ds_read_b32 v121, v104 offset:5632
	ds_read_b32 v122, v102 offset:112
	ds_read_b32 v123, v102 offset:4208
	ds_read_b32 v124, v106 offset:112
	ds_read_b32 v125, v106 offset:4464
	ds_read_b32 v126, v104 offset:1792
	ds_read_b32 v127, v104 offset:5888
	s_waitcnt lgkmcnt(6)
	v_mul_f32_e32 v108, v117, v119
	v_mul_f32_e32 v107, v116, v119
	v_fma_f32 v116, v116, v118, -v108
	v_fma_f32 v117, -v117, v118, -v107
	s_nop 1
	v_mfma_f32_16x16x4_f32 v[112:115], v116, v120, v[112:115]
	v_mfma_f32_16x16x4_f32 v[112:115], v117, v121, v[112:115]
	s_waitcnt lgkmcnt(0)
	v_mul_f32_e32 v108, v123, v125
	v_mul_f32_e32 v107, v122, v125
	v_fma_f32 v122, v122, v124, -v108
	v_fma_f32 v123, -v123, v124, -v107
	s_nop 1
	v_mfma_f32_16x16x4_f32 v[112:115], v122, v126, v[112:115]
	v_mfma_f32_16x16x4_f32 v[112:115], v123, v127, v[112:115]
	ds_read_b32 v116, v102 offset:128
	ds_read_b32 v117, v102 offset:4224
	ds_read_b32 v118, v106 offset:128
	ds_read_b32 v119, v106 offset:4480
	ds_read_b32 v120, v104 offset:2048
	ds_read_b32 v121, v104 offset:6144
	ds_read_b32 v122, v102 offset:144
	ds_read_b32 v123, v102 offset:4240
	ds_read_b32 v124, v106 offset:144
	ds_read_b32 v125, v106 offset:4496
	ds_read_b32 v126, v104 offset:2304
	ds_read_b32 v127, v104 offset:6400
	s_waitcnt lgkmcnt(6)
	v_mul_f32_e32 v108, v117, v119
	v_mul_f32_e32 v107, v116, v119
	v_fma_f32 v116, v116, v118, -v108
	v_fma_f32 v117, -v117, v118, -v107
	s_nop 1
	v_mfma_f32_16x16x4_f32 v[112:115], v116, v120, v[112:115]
	v_mfma_f32_16x16x4_f32 v[112:115], v117, v121, v[112:115]
	s_waitcnt lgkmcnt(0)
	v_mul_f32_e32 v108, v123, v125
	v_mul_f32_e32 v107, v122, v125
	v_fma_f32 v122, v122, v124, -v108
	v_fma_f32 v123, -v123, v124, -v107
	s_nop 1
	v_mfma_f32_16x16x4_f32 v[112:115], v122, v126, v[112:115]
	v_mfma_f32_16x16x4_f32 v[112:115], v123, v127, v[112:115]
	ds_read_b32 v116, v102 offset:160
	ds_read_b32 v117, v102 offset:4256
	ds_read_b32 v118, v106 offset:160
	ds_read_b32 v119, v106 offset:4512
	ds_read_b32 v120, v104 offset:2560
	ds_read_b32 v121, v104 offset:6656
	ds_read_b32 v122, v102 offset:176
	ds_read_b32 v123, v102 offset:4272
	ds_read_b32 v124, v106 offset:176
	ds_read_b32 v125, v106 offset:4528
	ds_read_b32 v126, v104 offset:2816
	ds_read_b32 v127, v104 offset:6912
	s_waitcnt lgkmcnt(6)
	v_mul_f32_e32 v108, v117, v119
	v_mul_f32_e32 v107, v116, v119
	v_fma_f32 v116, v116, v118, -v108
	v_fma_f32 v117, -v117, v118, -v107
	s_nop 1
	v_mfma_f32_16x16x4_f32 v[112:115], v116, v120, v[112:115]
	v_mfma_f32_16x16x4_f32 v[112:115], v117, v121, v[112:115]
	s_waitcnt lgkmcnt(0)
	v_mul_f32_e32 v108, v123, v125
	v_mul_f32_e32 v107, v122, v125
	v_fma_f32 v122, v122, v124, -v108
	v_fma_f32 v123, -v123, v124, -v107
	s_nop 1
	v_mfma_f32_16x16x4_f32 v[112:115], v122, v126, v[112:115]
	v_mfma_f32_16x16x4_f32 v[112:115], v123, v127, v[112:115]
	ds_read_b32 v116, v102 offset:192
	ds_read_b32 v117, v102 offset:4288
	ds_read_b32 v118, v106 offset:192
	ds_read_b32 v119, v106 offset:4544
	ds_read_b32 v120, v104 offset:3072
	ds_read_b32 v121, v104 offset:7168
	ds_read_b32 v122, v102 offset:208
	ds_read_b32 v123, v102 offset:4304
	ds_read_b32 v124, v106 offset:208
	ds_read_b32 v125, v106 offset:4560
	ds_read_b32 v126, v104 offset:3328
	ds_read_b32 v127, v104 offset:7424
	s_waitcnt lgkmcnt(6)
	v_mul_f32_e32 v108, v117, v119
	v_mul_f32_e32 v107, v116, v119
	v_fma_f32 v116, v116, v118, -v108
	v_fma_f32 v117, -v117, v118, -v107
	s_nop 1
	v_mfma_f32_16x16x4_f32 v[112:115], v116, v120, v[112:115]
	v_mfma_f32_16x16x4_f32 v[112:115], v117, v121, v[112:115]
	s_waitcnt lgkmcnt(0)
	v_mul_f32_e32 v108, v123, v125
	v_mul_f32_e32 v107, v122, v125
	v_fma_f32 v122, v122, v124, -v108
	v_fma_f32 v123, -v123, v124, -v107
	s_nop 1
	v_mfma_f32_16x16x4_f32 v[112:115], v122, v126, v[112:115]
	v_mfma_f32_16x16x4_f32 v[112:115], v123, v127, v[112:115]
	ds_read_b32 v116, v102 offset:224
	ds_read_b32 v117, v102 offset:4320
	ds_read_b32 v118, v106 offset:224
	ds_read_b32 v119, v106 offset:4576
	ds_read_b32 v120, v104 offset:3584
	ds_read_b32 v121, v104 offset:7680
	ds_read_b32 v122, v102 offset:240
	ds_read_b32 v123, v102 offset:4336
	ds_read_b32 v124, v106 offset:240
	ds_read_b32 v125, v106 offset:4592
	ds_read_b32 v126, v104 offset:3840
	ds_read_b32 v127, v104 offset:7936
	s_waitcnt lgkmcnt(6)
	v_mul_f32_e32 v108, v117, v119
	v_mul_f32_e32 v107, v116, v119
	v_fma_f32 v116, v116, v118, -v108
	v_fma_f32 v117, -v117, v118, -v107
	s_nop 1
	v_mfma_f32_16x16x4_f32 v[112:115], v116, v120, v[112:115]
	v_mfma_f32_16x16x4_f32 v[112:115], v117, v121, v[112:115]
	s_waitcnt lgkmcnt(0)
	v_mul_f32_e32 v108, v123, v125
	v_mul_f32_e32 v107, v122, v125
	v_fma_f32 v122, v122, v124, -v108
	v_fma_f32 v123, -v123, v124, -v107
	s_nop 1
	v_mfma_f32_16x16x4_f32 v[112:115], v122, v126, v[112:115]
	v_mfma_f32_16x16x4_f32 v[112:115], v123, v127, v[112:115]
	s_cmp_lg_u32 s10, 0
	s_cbranch_scc1 .Lkt_nodskip
	v_add_u32_e32 v108, s37, v100
	v_lshlrev_b32_e32 v108, 2, v108
	global_load_dword v109, v108, s[48:49]
	v_lshlrev_b32_e32 v107, 2, v101
	v_sub_u32_e32 v107, v100, v107
	s_waitcnt vmcnt(0)
	s_nop 7
	v_cmp_eq_u32_e32 vcc, 0, v107
	s_nop 1
	v_cndmask_b32_e32 v108, 0, v109, vcc
	v_add_f32_e32 v112, v112, v108
	v_cmp_eq_u32_e32 vcc, 1, v107
	s_nop 1
	v_cndmask_b32_e32 v108, 0, v109, vcc
	v_add_f32_e32 v113, v113, v108
	v_cmp_eq_u32_e32 vcc, 2, v107
	s_nop 1
	v_cndmask_b32_e32 v108, 0, v109, vcc
	v_add_f32_e32 v114, v114, v108
	v_cmp_eq_u32_e32 vcc, 3, v107
	s_nop 1
	v_cndmask_b32_e32 v108, 0, v109, vcc
	v_add_f32_e32 v115, v115, v108
.Lkt_nodskip:
	s_nop 7
	s_nop 7
	s_lshl_b32 s11, s10, 10
	v_add_u32_e32 v108, s11, v105
	ds_write_b32 v108, v112
	ds_write_b32 v108, v113 offset:64
	ds_write_b32 v108, v114 offset:128
	ds_write_b32 v108, v115 offset:192
	s_add_i32 s10, s10, 8
	s_cmp_lt_u32 s10, 17
	s_cbranch_scc1 .Lkt_tau
	s_mov_b64 s[40:41], 0

.LBB0_745:
	s_add_i32 s60, s60, s82
	s_add_i32 s55, s55, s82
	v_and_b32_e32 v178, 15, v181
	v_bfe_u32 v138, v181, 4, 2
	v_lshlrev_b32_e32 v141, 4, v178
	s_movk_i32 s20, 0x110
	v_mad_u32_u24 v141, v138, s20, v141
	v_lshlrev_b32_e32 v139, 2, v178
	s_movk_i32 s20, 0x440
	v_mad_u32_u24 v139, v138, s20, v139
	v_lshlrev_b32_e32 v138, 12, v138
	v_lshl_add_u32 v138, v178, 4, v138
	v_lshrrev_b32_e32 v178, 6, v181
	v_mul_u32_u24_e32 v178, 0x4400, v178
	v_add_u32_e32 v141, v141, v178
	v_add_u32_e32 v139, v139, v178
	v_bfe_u32 v178, v181, 6, 2
	v_lshl_add_u32 v138, v178, 8, v138
	v_lshrrev_b32_e32 v178, 8, v181
	v_lshl_add_u32 v138, v178, 19, v138
	s_lshl_b32 s20, s46, 20
	v_add_u32_e32 v138, s20, v138
	s_lshl_b32 s20, s6, 10
	v_add_u32_e32 v138, s20, v138
	s_mov_b32 s48, s78
	s_mov_b32 s49, s79
	s_mov_b32 s50, s78
	s_mov_b32 s51, s79
	global_load_dwordx4 v[130:133], v138, s[48:49]
	s_add_u32 s48, s48, 0x4000
	s_addc_u32 s49, s49, 0
	global_load_dwordx4 v[134:137], v138, s[48:49]
	s_add_u32 s48, s48, 0x4000
	s_addc_u32 s49, s49, 0
	global_load_dwordx4 v[142:145], v138, s[48:49]
	s_add_u32 s48, s48, 0x4000
	s_addc_u32 s49, s49, 0
	global_load_dwordx4 v[146:149], v138, s[48:49]
	s_add_u32 s48, s48, 0x4000
	s_addc_u32 s49, s49, 0
	global_load_dwordx4 v[150:153], v138, s[48:49]
	s_add_u32 s48, s48, 0x4000
	s_addc_u32 s49, s49, 0
	global_load_dwordx4 v[154:157], v138, s[48:49]
	s_add_u32 s48, s48, 0x4000
	s_addc_u32 s49, s49, 0
	global_load_dwordx4 v[158:161], v138, s[48:49]
	s_add_u32 s48, s48, 0x4000
	s_addc_u32 s49, s49, 0
	global_load_dwordx4 v[162:165], v138, s[48:49]
	s_add_u32 s48, s48, 0x4000
	s_addc_u32 s49, s49, 0
	global_load_dwordx4 v[166:169], v138, s[48:49]
	s_add_u32 s48, s48, 0x4000
	s_addc_u32 s49, s49, 0
	global_load_dwordx4 v[170:173], v138, s[48:49]
	s_add_u32 s48, s48, 0x4000
	s_addc_u32 s49, s49, 0
	global_load_dwordx4 v[174:177], v138, s[48:49]
	s_add_u32 s48, s48, 0x4000
	s_addc_u32 s49, s49, 0
	global_load_dwordx4 v[182:185], v138, s[48:49]
	s_add_u32 s48, s48, 0x4000
	s_addc_u32 s49, s49, 0
	global_load_dwordx4 v[186:189], v138, s[48:49]
	s_add_u32 s48, s48, 0x4000
	s_addc_u32 s49, s49, 0
	global_load_dwordx4 v[190:193], v138, s[48:49]
	s_add_u32 s48, s48, 0x4000
	s_addc_u32 s49, s49, 0
	global_load_dwordx4 v[194:197], v138, s[48:49]
	s_add_u32 s48, s48, 0x4000
	s_addc_u32 s49, s49, 0
	global_load_dwordx4 v[198:201], v138, s[48:49]
	s_add_u32 s48, s48, 0x4000
	s_addc_u32 s49, s49, 0
	ds_write_b32 v139, v124
	ds_write_b32 v139, v125 offset:272
	ds_write_b32 v139, v126 offset:544
	ds_write_b32 v139, v127 offset:816
	ds_write_b32 v139, v120 offset:64
	ds_write_b32 v139, v121 offset:336
	ds_write_b32 v139, v122 offset:608
	ds_write_b32 v139, v123 offset:880
	ds_write_b32 v139, v116 offset:128
	ds_write_b32 v139, v117 offset:400
	ds_write_b32 v139, v118 offset:672
	ds_write_b32 v139, v119 offset:944
	ds_write_b32 v139, v112 offset:192
	ds_write_b32 v139, v113 offset:464
	ds_write_b32 v139, v114 offset:736
	ds_write_b32 v139, v115 offset:1008
	ds_write_b32 v139, v108 offset:4352
	ds_write_b32 v139, v109 offset:4624
	ds_write_b32 v139, v110 offset:4896
	ds_write_b32 v139, v111 offset:5168
	ds_write_b32 v139, v104 offset:4416
	ds_write_b32 v139, v105 offset:4688
	ds_write_b32 v139, v106 offset:4960
	ds_write_b32 v139, v107 offset:5232
	ds_write_b32 v139, v100 offset:4480
	ds_write_b32 v139, v101 offset:4752
	ds_write_b32 v139, v102 offset:5024
	ds_write_b32 v139, v103 offset:5296
	ds_write_b32 v139, v96 offset:4544
	ds_write_b32 v139, v97 offset:4816
	ds_write_b32 v139, v98 offset:5088
	ds_write_b32 v139, v99 offset:5360
	ds_write_b32 v139, v92 offset:8704
	ds_write_b32 v139, v93 offset:8976
	ds_write_b32 v139, v94 offset:9248
	ds_write_b32 v139, v95 offset:9520
	ds_write_b32 v139, v88 offset:8768
	ds_write_b32 v139, v89 offset:9040
	ds_write_b32 v139, v90 offset:9312
	ds_write_b32 v139, v91 offset:9584
	ds_write_b32 v139, v84 offset:8832
	ds_write_b32 v139, v85 offset:9104
	ds_write_b32 v139, v86 offset:9376
	ds_write_b32 v139, v87 offset:9648
	ds_write_b32 v139, v80 offset:8896
	ds_write_b32 v139, v81 offset:9168
	ds_write_b32 v139, v82 offset:9440
	ds_write_b32 v139, v83 offset:9712
	ds_write_b32 v139, v76 offset:13056
	ds_write_b32 v139, v77 offset:13328
	ds_write_b32 v139, v78 offset:13600
	ds_write_b32 v139, v79 offset:13872
	ds_write_b32 v139, v72 offset:13120
	ds_write_b32 v139, v73 offset:13392
	ds_write_b32 v139, v74 offset:13664
	ds_write_b32 v139, v75 offset:13936
	ds_write_b32 v139, v68 offset:13184
	ds_write_b32 v139, v69 offset:13456
	ds_write_b32 v139, v70 offset:13728
	ds_write_b32 v139, v71 offset:14000
	ds_write_b32 v139, v64 offset:13248
	ds_write_b32 v139, v65 offset:13520
	ds_write_b32 v139, v66 offset:13792
	ds_write_b32 v139, v67 offset:14064
	s_waitcnt lgkmcnt(0)
	ds_read_b128 v[202:205], v141
	ds_read_b128 v[206:209], v141 offset:1088
	ds_read_b128 v[210:213], v141 offset:2176
	ds_read_b128 v[214:217], v141 offset:3264
	ds_read_b128 v[218:221], v141 offset:4352
	ds_read_b128 v[222:225], v141 offset:5440
	ds_read_b128 v[226:229], v141 offset:6528
	ds_read_b128 v[230:233], v141 offset:7616
	s_waitcnt vmcnt(15) lgkmcnt(7)
	v_pk_add_f32 v[130:131], v[130:131], v[202:203]
	v_pk_add_f32 v[132:133], v[132:133], v[204:205]
	global_store_dwordx4 v138, v[130:133], s[50:51] sc1
	s_add_u32 s50, s50, 0x4000
	s_addc_u32 s51, s51, 0
	s_waitcnt vmcnt(15) lgkmcnt(6)
	v_pk_add_f32 v[134:135], v[134:135], v[206:207]
	v_pk_add_f32 v[136:137], v[136:137], v[208:209]
	global_store_dwordx4 v138, v[134:137], s[50:51] sc1
	s_add_u32 s50, s50, 0x4000
	s_addc_u32 s51, s51, 0
	s_waitcnt vmcnt(15) lgkmcnt(5)
	v_pk_add_f32 v[142:143], v[142:143], v[210:211]
	v_pk_add_f32 v[144:145], v[144:145], v[212:213]
	global_store_dwordx4 v138, v[142:145], s[50:51] sc1
	s_add_u32 s50, s50, 0x4000
	s_addc_u32 s51, s51, 0
	s_waitcnt vmcnt(15) lgkmcnt(4)
	v_pk_add_f32 v[146:147], v[146:147], v[214:215]
	v_pk_add_f32 v[148:149], v[148:149], v[216:217]
	global_store_dwordx4 v138, v[146:149], s[50:51] sc1
	s_add_u32 s50, s50, 0x4000
	s_addc_u32 s51, s51, 0
	s_waitcnt vmcnt(15) lgkmcnt(3)
	v_pk_add_f32 v[150:151], v[150:151], v[218:219]
	v_pk_add_f32 v[152:153], v[152:153], v[220:221]
	global_store_dwordx4 v138, v[150:153], s[50:51] sc1
	s_add_u32 s50, s50, 0x4000
	s_addc_u32 s51, s51, 0
	s_waitcnt vmcnt(15) lgkmcnt(2)
	v_pk_add_f32 v[154:155], v[154:155], v[222:223]
	v_pk_add_f32 v[156:157], v[156:157], v[224:225]
	global_store_dwordx4 v138, v[154:157], s[50:51] sc1
	s_add_u32 s50, s50, 0x4000
	s_addc_u32 s51, s51, 0
	s_waitcnt vmcnt(15) lgkmcnt(1)
	v_pk_add_f32 v[158:159], v[158:159], v[226:227]
	v_pk_add_f32 v[160:161], v[160:161], v[228:229]
	global_store_dwordx4 v138, v[158:161], s[50:51] sc1
	s_add_u32 s50, s50, 0x4000
	s_addc_u32 s51, s51, 0
	s_waitcnt vmcnt(15) lgkmcnt(0)
	v_pk_add_f32 v[162:163], v[162:163], v[230:231]
	v_pk_add_f32 v[164:165], v[164:165], v[232:233]
	global_store_dwordx4 v138, v[162:165], s[50:51] sc1
	s_add_u32 s50, s50, 0x4000
	s_addc_u32 s51, s51, 0
	global_load_dwordx4 v[130:133], v138, s[48:49]
	s_add_u32 s48, s48, 0x4000
	s_addc_u32 s49, s49, 0
	global_load_dwordx4 v[134:137], v138, s[48:49]
	s_add_u32 s48, s48, 0x4000
	s_addc_u32 s49, s49, 0
	global_load_dwordx4 v[142:145], v138, s[48:49]
	s_add_u32 s48, s48, 0x4000
	s_addc_u32 s49, s49, 0
	global_load_dwordx4 v[146:149], v138, s[48:49]
	s_add_u32 s48, s48, 0x4000
	s_addc_u32 s49, s49, 0
	global_load_dwordx4 v[150:153], v138, s[48:49]
	s_add_u32 s48, s48, 0x4000
	s_addc_u32 s49, s49, 0
	global_load_dwordx4 v[154:157], v138, s[48:49]
	s_add_u32 s48, s48, 0x4000
	s_addc_u32 s49, s49, 0
	global_load_dwordx4 v[158:161], v138, s[48:49]
	s_add_u32 s48, s48, 0x4000
	s_addc_u32 s49, s49, 0
	global_load_dwordx4 v[162:165], v138, s[48:49]
	s_add_u32 s48, s48, 0x4000
	s_addc_u32 s49, s49, 0
	ds_read_b128 v[202:205], v141 offset:8704
	ds_read_b128 v[206:209], v141 offset:9792
	ds_read_b128 v[210:213], v141 offset:10880
	ds_read_b128 v[214:217], v141 offset:11968
	ds_read_b128 v[218:221], v141 offset:13056
	ds_read_b128 v[222:225], v141 offset:14144
	ds_read_b128 v[226:229], v141 offset:15232
	ds_read_b128 v[230:233], v141 offset:16320
	s_waitcnt vmcnt(15) lgkmcnt(7)
	v_pk_add_f32 v[166:167], v[166:167], v[202:203]
	v_pk_add_f32 v[168:169], v[168:169], v[204:205]
	global_store_dwordx4 v138, v[166:169], s[50:51] sc1
	s_add_u32 s50, s50, 0x4000
	s_addc_u32 s51, s51, 0
	s_waitcnt vmcnt(15) lgkmcnt(6)
	v_pk_add_f32 v[170:171], v[170:171], v[206:207]
	v_pk_add_f32 v[172:173], v[172:173], v[208:209]
	global_store_dwordx4 v138, v[170:173], s[50:51] sc1
	s_add_u32 s50, s50, 0x4000
	s_addc_u32 s51, s51, 0
	s_waitcnt vmcnt(15) lgkmcnt(5)
	v_pk_add_f32 v[174:175], v[174:175], v[210:211]
	v_pk_add_f32 v[176:177], v[176:177], v[212:213]
	global_store_dwordx4 v138, v[174:177], s[50:51] sc1
	s_add_u32 s50, s50, 0x4000
	s_addc_u32 s51, s51, 0
	s_waitcnt vmcnt(15) lgkmcnt(4)
	v_pk_add_f32 v[182:183], v[182:183], v[214:215]
	v_pk_add_f32 v[184:185], v[184:185], v[216:217]
	global_store_dwordx4 v138, v[182:185], s[50:51] sc1
	s_add_u32 s50, s50, 0x4000
	s_addc_u32 s51, s51, 0
	s_waitcnt vmcnt(15) lgkmcnt(3)
	v_pk_add_f32 v[186:187], v[186:187], v[218:219]
	v_pk_add_f32 v[188:189], v[188:189], v[220:221]
	global_store_dwordx4 v138, v[186:189], s[50:51] sc1
	s_add_u32 s50, s50, 0x4000
	s_addc_u32 s51, s51, 0
	s_waitcnt vmcnt(15) lgkmcnt(2)
	v_pk_add_f32 v[190:191], v[190:191], v[222:223]
	v_pk_add_f32 v[192:193], v[192:193], v[224:225]
	global_store_dwordx4 v138, v[190:193], s[50:51] sc1
	s_add_u32 s50, s50, 0x4000
	s_addc_u32 s51, s51, 0
	s_waitcnt vmcnt(15) lgkmcnt(1)
	v_pk_add_f32 v[194:195], v[194:195], v[226:227]
	v_pk_add_f32 v[196:197], v[196:197], v[228:229]
	global_store_dwordx4 v138, v[194:197], s[50:51] sc1
	s_add_u32 s50, s50, 0x4000
	s_addc_u32 s51, s51, 0
	s_waitcnt vmcnt(15) lgkmcnt(0)
	v_pk_add_f32 v[198:199], v[198:199], v[230:231]
	v_pk_add_f32 v[200:201], v[200:201], v[232:233]
	global_store_dwordx4 v138, v[198:201], s[50:51] sc1
	s_add_u32 s50, s50, 0x4000
	s_addc_u32 s51, s51, 0
	s_waitcnt lgkmcnt(0)
	global_load_dwordx4 v[166:169], v138, s[48:49]
	s_add_u32 s48, s48, 0x4000
	s_addc_u32 s49, s49, 0
	global_load_dwordx4 v[170:173], v138, s[48:49]
	s_add_u32 s48, s48, 0x4000
	s_addc_u32 s49, s49, 0
	global_load_dwordx4 v[174:177], v138, s[48:49]
	s_add_u32 s48, s48, 0x4000
	s_addc_u32 s49, s49, 0
	global_load_dwordx4 v[182:185], v138, s[48:49]
	s_add_u32 s48, s48, 0x4000
	s_addc_u32 s49, s49, 0
	global_load_dwordx4 v[186:189], v138, s[48:49]
	s_add_u32 s48, s48, 0x4000
	s_addc_u32 s49, s49, 0
	global_load_dwordx4 v[190:193], v138, s[48:49]
	s_add_u32 s48, s48, 0x4000
	s_addc_u32 s49, s49, 0
	global_load_dwordx4 v[194:197], v138, s[48:49]
	s_add_u32 s48, s48, 0x4000
	s_addc_u32 s49, s49, 0
	global_load_dwordx4 v[198:201], v138, s[48:49]
	s_add_u32 s48, s48, 0x4000
	s_addc_u32 s49, s49, 0
	ds_write_b32 v139, v60
	ds_write_b32 v139, v61 offset:272
	ds_write_b32 v139, v62 offset:544
	ds_write_b32 v139, v63 offset:816
	ds_write_b32 v139, v56 offset:64
	ds_write_b32 v139, v57 offset:336
	ds_write_b32 v139, v58 offset:608
	ds_write_b32 v139, v59 offset:880
	ds_write_b32 v139, v52 offset:128
	ds_write_b32 v139, v53 offset:400
	ds_write_b32 v139, v54 offset:672
	ds_write_b32 v139, v55 offset:944
	ds_write_b32 v139, v48 offset:192
	ds_write_b32 v139, v49 offset:464
	ds_write_b32 v139, v50 offset:736
	ds_write_b32 v139, v51 offset:1008
	ds_write_b32 v139, v44 offset:4352
	ds_write_b32 v139, v45 offset:4624
	ds_write_b32 v139, v46 offset:4896
	ds_write_b32 v139, v47 offset:5168
	ds_write_b32 v139, v32 offset:4416
	ds_write_b32 v139, v33 offset:4688
	ds_write_b32 v139, v34 offset:4960
	ds_write_b32 v139, v35 offset:5232
	ds_write_b32 v139, v28 offset:4480
	ds_write_b32 v139, v29 offset:4752
	ds_write_b32 v139, v30 offset:5024
	ds_write_b32 v139, v31 offset:5296
	ds_write_b32 v139, v24 offset:4544
	ds_write_b32 v139, v25 offset:4816
	ds_write_b32 v139, v26 offset:5088
	ds_write_b32 v139, v27 offset:5360
	ds_write_b32 v139, v20 offset:8704
	ds_write_b32 v139, v21 offset:8976
	ds_write_b32 v139, v22 offset:9248
	ds_write_b32 v139, v23 offset:9520
	ds_write_b32 v139, v16 offset:8768
	ds_write_b32 v139, v17 offset:9040
	ds_write_b32 v139, v18 offset:9312
	ds_write_b32 v139, v19 offset:9584
	ds_write_b32 v139, v12 offset:8832
	ds_write_b32 v139, v13 offset:9104
	ds_write_b32 v139, v14 offset:9376
	ds_write_b32 v139, v15 offset:9648
	ds_write_b32 v139, v8 offset:8896
	ds_write_b32 v139, v9 offset:9168
	ds_write_b32 v139, v10 offset:9440
	ds_write_b32 v139, v11 offset:9712
	ds_write_b32 v139, v4 offset:13056
	ds_write_b32 v139, v5 offset:13328
	ds_write_b32 v139, v6 offset:13600
	ds_write_b32 v139, v7 offset:13872
	ds_write_b32 v139, v0 offset:13120
	ds_write_b32 v139, v1 offset:13392
	ds_write_b32 v139, v2 offset:13664
	ds_write_b32 v139, v3 offset:13936
	ds_write_b32 v139, v40 offset:13184
	ds_write_b32 v139, v41 offset:13456
	ds_write_b32 v139, v42 offset:13728
	ds_write_b32 v139, v43 offset:14000
	ds_write_b32 v139, v36 offset:13248
	ds_write_b32 v139, v37 offset:13520
	ds_write_b32 v139, v38 offset:13792
	ds_write_b32 v139, v39 offset:14064
	s_waitcnt lgkmcnt(0)
	ds_read_b128 v[202:205], v141
	ds_read_b128 v[206:209], v141 offset:1088
	ds_read_b128 v[210:213], v141 offset:2176
	ds_read_b128 v[214:217], v141 offset:3264
	ds_read_b128 v[218:221], v141 offset:4352
	ds_read_b128 v[222:225], v141 offset:5440
	ds_read_b128 v[226:229], v141 offset:6528
	ds_read_b128 v[230:233], v141 offset:7616
	s_waitcnt vmcnt(15) lgkmcnt(7)
	v_pk_add_f32 v[130:131], v[130:131], v[202:203]
	v_pk_add_f32 v[132:133], v[132:133], v[204:205]
	global_store_dwordx4 v138, v[130:133], s[50:51] sc1
	s_add_u32 s50, s50, 0x4000
	s_addc_u32 s51, s51, 0
	s_waitcnt vmcnt(15) lgkmcnt(6)
	v_pk_add_f32 v[134:135], v[134:135], v[206:207]
	v_pk_add_f32 v[136:137], v[136:137], v[208:209]
	global_store_dwordx4 v138, v[134:137], s[50:51] sc1
	s_add_u32 s50, s50, 0x4000
	s_addc_u32 s51, s51, 0
	s_waitcnt vmcnt(15) lgkmcnt(5)
	v_pk_add_f32 v[142:143], v[142:143], v[210:211]
	v_pk_add_f32 v[144:145], v[144:145], v[212:213]
	global_store_dwordx4 v138, v[142:145], s[50:51] sc1
	s_add_u32 s50, s50, 0x4000
	s_addc_u32 s51, s51, 0
	s_waitcnt vmcnt(15) lgkmcnt(4)
	v_pk_add_f32 v[146:147], v[146:147], v[214:215]
	v_pk_add_f32 v[148:149], v[148:149], v[216:217]
	global_store_dwordx4 v138, v[146:149], s[50:51] sc1
	s_add_u32 s50, s50, 0x4000
	s_addc_u32 s51, s51, 0
	s_waitcnt vmcnt(15) lgkmcnt(3)
	v_pk_add_f32 v[150:151], v[150:151], v[218:219]
	v_pk_add_f32 v[152:153], v[152:153], v[220:221]
	global_store_dwordx4 v138, v[150:153], s[50:51] sc1
	s_add_u32 s50, s50, 0x4000
	s_addc_u32 s51, s51, 0
	s_waitcnt vmcnt(15) lgkmcnt(2)
	v_pk_add_f32 v[154:155], v[154:155], v[222:223]
	v_pk_add_f32 v[156:157], v[156:157], v[224:225]
	global_store_dwordx4 v138, v[154:157], s[50:51] sc1
	s_add_u32 s50, s50, 0x4000
	s_addc_u32 s51, s51, 0
	s_waitcnt vmcnt(15) lgkmcnt(1)
	v_pk_add_f32 v[158:159], v[158:159], v[226:227]
	v_pk_add_f32 v[160:161], v[160:161], v[228:229]
	global_store_dwordx4 v138, v[158:161], s[50:51] sc1
	s_add_u32 s50, s50, 0x4000
	s_addc_u32 s51, s51, 0
	s_waitcnt vmcnt(15) lgkmcnt(0)
	v_pk_add_f32 v[162:163], v[162:163], v[230:231]
	v_pk_add_f32 v[164:165], v[164:165], v[232:233]
	global_store_dwordx4 v138, v[162:165], s[50:51] sc1
	s_add_u32 s50, s50, 0x4000
	s_addc_u32 s51, s51, 0
	ds_read_b128 v[202:205], v141 offset:8704
	ds_read_b128 v[206:209], v141 offset:9792
	ds_read_b128 v[210:213], v141 offset:10880
	ds_read_b128 v[214:217], v141 offset:11968
	ds_read_b128 v[218:221], v141 offset:13056
	ds_read_b128 v[222:225], v141 offset:14144
	ds_read_b128 v[226:229], v141 offset:15232
	ds_read_b128 v[230:233], v141 offset:16320
	s_waitcnt vmcnt(7) lgkmcnt(7)
	v_pk_add_f32 v[166:167], v[166:167], v[202:203]
	v_pk_add_f32 v[168:169], v[168:169], v[204:205]
	global_store_dwordx4 v138, v[166:169], s[50:51] sc1
	s_add_u32 s50, s50, 0x4000
	s_addc_u32 s51, s51, 0
	s_waitcnt vmcnt(7) lgkmcnt(6)
	v_pk_add_f32 v[170:171], v[170:171], v[206:207]
	v_pk_add_f32 v[172:173], v[172:173], v[208:209]
	global_store_dwordx4 v138, v[170:173], s[50:51] sc1
	s_add_u32 s50, s50, 0x4000
	s_addc_u32 s51, s51, 0
	s_waitcnt vmcnt(7) lgkmcnt(5)
	v_pk_add_f32 v[174:175], v[174:175], v[210:211]
	v_pk_add_f32 v[176:177], v[176:177], v[212:213]
	global_store_dwordx4 v138, v[174:177], s[50:51] sc1
	s_add_u32 s50, s50, 0x4000
	s_addc_u32 s51, s51, 0
	s_waitcnt vmcnt(7) lgkmcnt(4)
	v_pk_add_f32 v[182:183], v[182:183], v[214:215]
	v_pk_add_f32 v[184:185], v[184:185], v[216:217]
	global_store_dwordx4 v138, v[182:185], s[50:51] sc1
	s_add_u32 s50, s50, 0x4000
	s_addc_u32 s51, s51, 0
	s_waitcnt vmcnt(7) lgkmcnt(3)
	v_pk_add_f32 v[186:187], v[186:187], v[218:219]
	v_pk_add_f32 v[188:189], v[188:189], v[220:221]
	global_store_dwordx4 v138, v[186:189], s[50:51] sc1
	s_add_u32 s50, s50, 0x4000
	s_addc_u32 s51, s51, 0
	s_waitcnt vmcnt(7) lgkmcnt(2)
	v_pk_add_f32 v[190:191], v[190:191], v[222:223]
	v_pk_add_f32 v[192:193], v[192:193], v[224:225]
	global_store_dwordx4 v138, v[190:193], s[50:51] sc1
	s_add_u32 s50, s50, 0x4000
	s_addc_u32 s51, s51, 0
	s_waitcnt vmcnt(7) lgkmcnt(1)
	v_pk_add_f32 v[194:195], v[194:195], v[226:227]
	v_pk_add_f32 v[196:197], v[196:197], v[228:229]
	global_store_dwordx4 v138, v[194:197], s[50:51] sc1
	s_add_u32 s50, s50, 0x4000
	s_addc_u32 s51, s51, 0
	s_waitcnt vmcnt(7) lgkmcnt(0)
	v_pk_add_f32 v[198:199], v[198:199], v[230:231]
	v_pk_add_f32 v[200:201], v[200:201], v[232:233]
	global_store_dwordx4 v138, v[198:201], s[50:51] sc1
	s_add_u32 s50, s50, 0x4000
	s_addc_u32 s51, s51, 0
	s_cmpk_lt_i32 s60, 0x100
	s_cbranch_scc0 .LBB0_752

.LBB0_1264:
	v_cmp_le_i32_e32 vcc, s43, v207
	s_and_saveexec_b64 s[10:11], vcc
	s_cbranch_execz .LBB0_1261
	ds_read_b128 v[2:5], v241
	ds_read_b128 v[6:9], v241 offset:32
	ds_read_b128 v[10:13], v241 offset:64
	ds_read_b128 v[248:251], v241 offset:96
	s_waitcnt lgkmcnt(3)
	v_mfma_f32_32x32x16_bf16 v[96:111], v[2:5], v[112:115], 0
	ds_read_b128 v[2:5], v241 offset:128
	s_waitcnt lgkmcnt(3)
	v_mfma_f32_32x32x16_bf16 v[96:111], v[6:9], v[116:119], v[96:111]
	ds_read_b128 v[6:9], v241 offset:160
	s_waitcnt lgkmcnt(3)
	v_mfma_f32_32x32x16_bf16 v[96:111], v[10:13], v[120:123], v[96:111]
	ds_read_b128 v[10:13], v241 offset:192
	s_waitcnt lgkmcnt(3)
	v_mfma_f32_32x32x16_bf16 v[96:111], v[248:251], v[124:127], v[96:111]
	ds_read_b128 v[248:251], v241 offset:224
	s_waitcnt lgkmcnt(3)
	v_mfma_f32_32x32x16_bf16 v[96:111], v[2:5], v[128:131], v[96:111]
	ds_read_b128 v[2:5], v241 offset:256
	s_waitcnt lgkmcnt(3)
	v_mfma_f32_32x32x16_bf16 v[96:111], v[6:9], v[132:135], v[96:111]
	ds_read_b128 v[6:9], v241 offset:288
	s_waitcnt lgkmcnt(3)
	v_mfma_f32_32x32x16_bf16 v[96:111], v[10:13], v[136:139], v[96:111]
	ds_read_b128 v[10:13], v241 offset:320
	s_waitcnt lgkmcnt(3)
	v_mfma_f32_32x32x16_bf16 v[96:111], v[248:251], v[140:143], v[96:111]
	ds_read_b128 v[248:251], v241 offset:352
	s_waitcnt lgkmcnt(3)
	v_mfma_f32_32x32x16_bf16 v[96:111], v[2:5], v[144:147], v[96:111]
	ds_read_b128 v[2:5], v241 offset:12800
	s_waitcnt lgkmcnt(3)
	v_mfma_f32_32x32x16_bf16 v[96:111], v[6:9], v[148:151], v[96:111]
	ds_read_b128 v[6:9], v241 offset:12832
	s_waitcnt lgkmcnt(3)
	v_mfma_f32_32x32x16_bf16 v[96:111], v[10:13], v[152:155], v[96:111]
	ds_read_b128 v[10:13], v241 offset:12864
	s_waitcnt lgkmcnt(3)
	v_mfma_f32_32x32x16_bf16 v[96:111], v[248:251], v[156:159], v[96:111]
	ds_read_b128 v[248:251], v241 offset:12896
	s_waitcnt lgkmcnt(3)
	v_mfma_f32_32x32x16_bf16 v[80:95], v[2:5], v[112:115], 0
	ds_read_b128 v[2:5], v241 offset:12928
	s_waitcnt lgkmcnt(3)
	v_mfma_f32_32x32x16_bf16 v[80:95], v[6:9], v[116:119], v[80:95]
	ds_read_b128 v[6:9], v241 offset:12960
	s_waitcnt lgkmcnt(3)
	v_mfma_f32_32x32x16_bf16 v[80:95], v[10:13], v[120:123], v[80:95]
	ds_read_b128 v[10:13], v241 offset:12992
	s_waitcnt lgkmcnt(3)
	v_mfma_f32_32x32x16_bf16 v[80:95], v[248:251], v[124:127], v[80:95]
	ds_read_b128 v[248:251], v241 offset:13024
	s_waitcnt lgkmcnt(3)
	v_mfma_f32_32x32x16_bf16 v[80:95], v[2:5], v[128:131], v[80:95]
	ds_read_b128 v[2:5], v241 offset:13056
	s_waitcnt lgkmcnt(3)
	v_mfma_f32_32x32x16_bf16 v[80:95], v[6:9], v[132:135], v[80:95]
	ds_read_b128 v[6:9], v241 offset:13088
	s_waitcnt lgkmcnt(3)
	v_mfma_f32_32x32x16_bf16 v[80:95], v[10:13], v[136:139], v[80:95]
	ds_read_b128 v[10:13], v241 offset:13120
	s_waitcnt lgkmcnt(3)
	v_mfma_f32_32x32x16_bf16 v[80:95], v[248:251], v[140:143], v[80:95]
	ds_read_b128 v[248:251], v241 offset:13152
	s_waitcnt lgkmcnt(3)
	v_mfma_f32_32x32x16_bf16 v[80:95], v[2:5], v[144:147], v[80:95]
	s_waitcnt lgkmcnt(2)
	v_mfma_f32_32x32x16_bf16 v[80:95], v[6:9], v[148:151], v[80:95]
	s_waitcnt lgkmcnt(1)
	v_mfma_f32_32x32x16_bf16 v[80:95], v[10:13], v[152:155], v[80:95]
	s_waitcnt lgkmcnt(0)
	v_mfma_f32_32x32x16_bf16 v[80:95], v[248:251], v[156:159], v[80:95]
	s_add_i32 s8, s43, 63
	v_cmp_gt_i32_e32 vcc, s8, v206
	s_and_saveexec_b64 s[12:13], vcc
	s_cbranch_execz .LBB0_1267
	v_add_u32_e32 v0, s43, v217
	v_cmp_gt_i32_e32 vcc, v0, v208
	s_nop 1
	v_cndmask_b32_e32 v2, v96, v244, vcc
	v_cmp_lt_i32_e32 vcc, v0, v208
	s_nop 1
	v_cndmask_b32_e32 v96, v2, v96, vcc
	v_add_u32_e32 v2, 2, v0
	v_cndmask_b32_e32 v97, v244, v97, vcc
	v_cmp_le_i32_e32 vcc, v2, v208
	v_add_u32_e32 v2, 3, v0
	s_nop 0
	v_cndmask_b32_e32 v98, v244, v98, vcc
	v_cmp_le_i32_e32 vcc, v2, v208
	v_add_u32_e32 v2, 8, v0
	s_nop 0
	v_cndmask_b32_e32 v99, v244, v99, vcc
	v_cmp_le_i32_e32 vcc, v2, v208
	v_add_u32_e32 v2, 9, v0
	s_nop 0
	v_cndmask_b32_e32 v100, v244, v100, vcc
	v_cmp_le_i32_e32 vcc, v2, v208
	v_add_u32_e32 v2, 10, v0
	s_nop 0
	v_cndmask_b32_e32 v101, v244, v101, vcc
	v_cmp_le_i32_e32 vcc, v2, v208
	v_add_u32_e32 v2, 11, v0
	s_nop 0
	v_cndmask_b32_e32 v102, v244, v102, vcc
	v_cmp_le_i32_e32 vcc, v2, v208
	v_add_u32_e32 v2, 16, v0
	s_nop 0
	v_cndmask_b32_e32 v103, v244, v103, vcc
	v_cmp_le_i32_e32 vcc, v2, v208
	v_add_u32_e32 v2, 17, v0
	s_nop 0
	v_cndmask_b32_e32 v104, v244, v104, vcc
	v_cmp_le_i32_e32 vcc, v2, v208
	v_add_u32_e32 v2, 18, v0
	s_nop 0
	v_cndmask_b32_e32 v105, v244, v105, vcc
	v_cmp_le_i32_e32 vcc, v2, v208
	v_add_u32_e32 v2, 19, v0
	s_nop 0
	v_cndmask_b32_e32 v106, v244, v106, vcc
	v_cmp_le_i32_e32 vcc, v2, v208
	v_add_u32_e32 v2, 24, v0
	s_nop 0
	v_cndmask_b32_e32 v107, v244, v107, vcc
	v_cmp_le_i32_e32 vcc, v2, v208
	v_add_u32_e32 v2, 25, v0
	s_nop 0
	v_cndmask_b32_e32 v108, v244, v108, vcc
	v_cmp_le_i32_e32 vcc, v2, v208
	v_add_u32_e32 v2, 26, v0
	s_nop 0
	v_cndmask_b32_e32 v109, v244, v109, vcc
	v_cmp_le_i32_e32 vcc, v2, v208
	v_add_u32_e32 v2, 27, v0
	s_nop 0
	v_cndmask_b32_e32 v110, v244, v110, vcc
	v_cmp_le_i32_e32 vcc, v2, v208
	v_add_u32_e32 v2, 32, v0
	s_nop 0
	v_cndmask_b32_e32 v111, v244, v111, vcc
	v_cmp_le_i32_e32 vcc, v2, v208
	v_add_u32_e32 v2, 33, v0
	s_nop 0
	v_cndmask_b32_e32 v80, v244, v80, vcc
	v_cmp_le_i32_e32 vcc, v2, v208
	v_add_u32_e32 v2, 34, v0
	s_nop 0
	v_cndmask_b32_e32 v81, v244, v81, vcc
	v_cmp_le_i32_e32 vcc, v2, v208
	v_add_u32_e32 v2, 35, v0
	s_nop 0
	v_cndmask_b32_e32 v82, v244, v82, vcc
	v_cmp_le_i32_e32 vcc, v2, v208
	v_add_u32_e32 v2, 40, v0
	s_nop 0
	v_cndmask_b32_e32 v83, v244, v83, vcc
	v_cmp_le_i32_e32 vcc, v2, v208
	v_add_u32_e32 v2, 41, v0
	s_nop 0
	v_cndmask_b32_e32 v84, v244, v84, vcc
	v_cmp_le_i32_e32 vcc, v2, v208
	v_add_u32_e32 v2, 42, v0
	s_nop 0
	v_cndmask_b32_e32 v85, v244, v85, vcc
	v_cmp_le_i32_e32 vcc, v2, v208
	v_add_u32_e32 v2, 43, v0
	s_nop 0
	v_cndmask_b32_e32 v86, v244, v86, vcc
	v_cmp_le_i32_e32 vcc, v2, v208
	v_add_u32_e32 v2, 48, v0
	s_nop 0
	v_cndmask_b32_e32 v87, v244, v87, vcc
	v_cmp_le_i32_e32 vcc, v2, v208
	v_add_u32_e32 v2, 49, v0
	s_nop 0
	v_cndmask_b32_e32 v88, v244, v88, vcc
	v_cmp_le_i32_e32 vcc, v2, v208
	v_add_u32_e32 v2, 50, v0
	s_nop 0
	v_cndmask_b32_e32 v89, v244, v89, vcc
	v_cmp_le_i32_e32 vcc, v2, v208
	v_add_u32_e32 v2, 51, v0
	s_nop 0
	v_cndmask_b32_e32 v90, v244, v90, vcc
	v_cmp_le_i32_e32 vcc, v2, v208
	v_add_u32_e32 v2, 56, v0
	s_nop 0
	v_cndmask_b32_e32 v91, v244, v91, vcc
	v_cmp_le_i32_e32 vcc, v2, v208
	v_add_u32_e32 v2, 57, v0
	s_nop 0
	v_cndmask_b32_e32 v92, v244, v92, vcc
	v_cmp_le_i32_e32 vcc, v2, v208
	v_add_u32_e32 v2, 58, v0
	v_add_u32_e32 v0, 59, v0
	v_cndmask_b32_e32 v93, v244, v93, vcc
	v_cmp_le_i32_e32 vcc, v2, v208
	s_nop 1
	v_cndmask_b32_e32 v94, v244, v94, vcc
	v_cmp_le_i32_e32 vcc, v0, v208
	s_nop 1
	v_cndmask_b32_e32 v95, v244, v95, vcc

.LBB0_1330:
	s_add_i32 s58, s58, s82
	s_add_i32 s57, s57, s82
	v_and_b32_e32 v178, 15, v181
	v_bfe_u32 v138, v181, 4, 2
	v_lshlrev_b32_e32 v141, 4, v178
	s_movk_i32 s20, 0x110
	v_mad_u32_u24 v141, v138, s20, v141
	v_lshlrev_b32_e32 v139, 2, v178
	s_movk_i32 s20, 0x440
	v_mad_u32_u24 v139, v138, s20, v139
	v_lshlrev_b32_e32 v138, 12, v138
	v_lshl_add_u32 v138, v178, 4, v138
	v_lshrrev_b32_e32 v178, 6, v181
	v_mul_u32_u24_e32 v178, 0x4400, v178
	v_add_u32_e32 v141, v141, v178
	v_add_u32_e32 v139, v139, v178
	v_bfe_u32 v178, v181, 6, 2
	v_lshl_add_u32 v138, v178, 8, v138
	v_lshrrev_b32_e32 v178, 8, v181
	v_lshl_add_u32 v138, v178, 19, v138
	s_lshl_b32 s20, s42, 20
	v_add_u32_e32 v138, s20, v138
	s_lshl_b32 s20, s4, 10
	v_add_u32_e32 v138, s20, v138
	s_mov_b32 s44, s78
	s_mov_b32 s45, s79
	s_mov_b32 s46, s78
	s_mov_b32 s47, s79
	global_load_dwordx4 v[130:133], v138, s[44:45]
	s_add_u32 s44, s44, 0x4000
	s_addc_u32 s45, s45, 0
	global_load_dwordx4 v[134:137], v138, s[44:45]
	s_add_u32 s44, s44, 0x4000
	s_addc_u32 s45, s45, 0
	global_load_dwordx4 v[142:145], v138, s[44:45]
	s_add_u32 s44, s44, 0x4000
	s_addc_u32 s45, s45, 0
	global_load_dwordx4 v[146:149], v138, s[44:45]
	s_add_u32 s44, s44, 0x4000
	s_addc_u32 s45, s45, 0
	global_load_dwordx4 v[150:153], v138, s[44:45]
	s_add_u32 s44, s44, 0x4000
	s_addc_u32 s45, s45, 0
	global_load_dwordx4 v[154:157], v138, s[44:45]
	s_add_u32 s44, s44, 0x4000
	s_addc_u32 s45, s45, 0
	global_load_dwordx4 v[158:161], v138, s[44:45]
	s_add_u32 s44, s44, 0x4000
	s_addc_u32 s45, s45, 0
	global_load_dwordx4 v[162:165], v138, s[44:45]
	s_add_u32 s44, s44, 0x4000
	s_addc_u32 s45, s45, 0
	global_load_dwordx4 v[166:169], v138, s[44:45]
	s_add_u32 s44, s44, 0x4000
	s_addc_u32 s45, s45, 0
	global_load_dwordx4 v[170:173], v138, s[44:45]
	s_add_u32 s44, s44, 0x4000
	s_addc_u32 s45, s45, 0
	global_load_dwordx4 v[174:177], v138, s[44:45]
	s_add_u32 s44, s44, 0x4000
	s_addc_u32 s45, s45, 0
	global_load_dwordx4 v[182:185], v138, s[44:45]
	s_add_u32 s44, s44, 0x4000
	s_addc_u32 s45, s45, 0
	global_load_dwordx4 v[186:189], v138, s[44:45]
	s_add_u32 s44, s44, 0x4000
	s_addc_u32 s45, s45, 0
	global_load_dwordx4 v[190:193], v138, s[44:45]
	s_add_u32 s44, s44, 0x4000
	s_addc_u32 s45, s45, 0
	global_load_dwordx4 v[194:197], v138, s[44:45]
	s_add_u32 s44, s44, 0x4000
	s_addc_u32 s45, s45, 0
	global_load_dwordx4 v[198:201], v138, s[44:45]
	s_add_u32 s44, s44, 0x4000
	s_addc_u32 s45, s45, 0
	ds_write_b32 v139, v124
	ds_write_b32 v139, v125 offset:272
	ds_write_b32 v139, v126 offset:544
	ds_write_b32 v139, v127 offset:816
	ds_write_b32 v139, v120 offset:64
	ds_write_b32 v139, v121 offset:336
	ds_write_b32 v139, v122 offset:608
	ds_write_b32 v139, v123 offset:880
	ds_write_b32 v139, v116 offset:128
	ds_write_b32 v139, v117 offset:400
	ds_write_b32 v139, v118 offset:672
	ds_write_b32 v139, v119 offset:944
	ds_write_b32 v139, v112 offset:192
	ds_write_b32 v139, v113 offset:464
	ds_write_b32 v139, v114 offset:736
	ds_write_b32 v139, v115 offset:1008
	ds_write_b32 v139, v108 offset:4352
	ds_write_b32 v139, v109 offset:4624
	ds_write_b32 v139, v110 offset:4896
	ds_write_b32 v139, v111 offset:5168
	ds_write_b32 v139, v104 offset:4416
	ds_write_b32 v139, v105 offset:4688
	ds_write_b32 v139, v106 offset:4960
	ds_write_b32 v139, v107 offset:5232
	ds_write_b32 v139, v100 offset:4480
	ds_write_b32 v139, v101 offset:4752
	ds_write_b32 v139, v102 offset:5024
	ds_write_b32 v139, v103 offset:5296
	ds_write_b32 v139, v96 offset:4544
	ds_write_b32 v139, v97 offset:4816
	ds_write_b32 v139, v98 offset:5088
	ds_write_b32 v139, v99 offset:5360
	ds_write_b32 v139, v92 offset:8704
	ds_write_b32 v139, v93 offset:8976
	ds_write_b32 v139, v94 offset:9248
	ds_write_b32 v139, v95 offset:9520
	ds_write_b32 v139, v88 offset:8768
	ds_write_b32 v139, v89 offset:9040
	ds_write_b32 v139, v90 offset:9312
	ds_write_b32 v139, v91 offset:9584
	ds_write_b32 v139, v84 offset:8832
	ds_write_b32 v139, v85 offset:9104
	ds_write_b32 v139, v86 offset:9376
	ds_write_b32 v139, v87 offset:9648
	ds_write_b32 v139, v80 offset:8896
	ds_write_b32 v139, v81 offset:9168
	ds_write_b32 v139, v82 offset:9440
	ds_write_b32 v139, v83 offset:9712
	ds_write_b32 v139, v76 offset:13056
	ds_write_b32 v139, v77 offset:13328
	ds_write_b32 v139, v78 offset:13600
	ds_write_b32 v139, v79 offset:13872
	ds_write_b32 v139, v72 offset:13120
	ds_write_b32 v139, v73 offset:13392
	ds_write_b32 v139, v74 offset:13664
	ds_write_b32 v139, v75 offset:13936
	ds_write_b32 v139, v68 offset:13184
	ds_write_b32 v139, v69 offset:13456
	ds_write_b32 v139, v70 offset:13728
	ds_write_b32 v139, v71 offset:14000
	ds_write_b32 v139, v64 offset:13248
	ds_write_b32 v139, v65 offset:13520
	ds_write_b32 v139, v66 offset:13792
	ds_write_b32 v139, v67 offset:14064
	s_waitcnt lgkmcnt(0)
	ds_read_b128 v[202:205], v141
	ds_read_b128 v[206:209], v141 offset:1088
	ds_read_b128 v[210:213], v141 offset:2176
	ds_read_b128 v[214:217], v141 offset:3264
	ds_read_b128 v[218:221], v141 offset:4352
	ds_read_b128 v[222:225], v141 offset:5440
	ds_read_b128 v[226:229], v141 offset:6528
	ds_read_b128 v[230:233], v141 offset:7616
	s_waitcnt vmcnt(15) lgkmcnt(7)
	v_pk_add_f32 v[130:131], v[130:131], v[202:203]
	v_pk_add_f32 v[132:133], v[132:133], v[204:205]
	global_store_dwordx4 v138, v[130:133], s[46:47] sc1
	s_add_u32 s46, s46, 0x4000
	s_addc_u32 s47, s47, 0
	s_waitcnt vmcnt(15) lgkmcnt(6)
	v_pk_add_f32 v[134:135], v[134:135], v[206:207]
	v_pk_add_f32 v[136:137], v[136:137], v[208:209]
	global_store_dwordx4 v138, v[134:137], s[46:47] sc1
	s_add_u32 s46, s46, 0x4000
	s_addc_u32 s47, s47, 0
	s_waitcnt vmcnt(15) lgkmcnt(5)
	v_pk_add_f32 v[142:143], v[142:143], v[210:211]
	v_pk_add_f32 v[144:145], v[144:145], v[212:213]
	global_store_dwordx4 v138, v[142:145], s[46:47] sc1
	s_add_u32 s46, s46, 0x4000
	s_addc_u32 s47, s47, 0
	s_waitcnt vmcnt(15) lgkmcnt(4)
	v_pk_add_f32 v[146:147], v[146:147], v[214:215]
	v_pk_add_f32 v[148:149], v[148:149], v[216:217]
	global_store_dwordx4 v138, v[146:149], s[46:47] sc1
	s_add_u32 s46, s46, 0x4000
	s_addc_u32 s47, s47, 0
	s_waitcnt vmcnt(15) lgkmcnt(3)
	v_pk_add_f32 v[150:151], v[150:151], v[218:219]
	v_pk_add_f32 v[152:153], v[152:153], v[220:221]
	global_store_dwordx4 v138, v[150:153], s[46:47] sc1
	s_add_u32 s46, s46, 0x4000
	s_addc_u32 s47, s47, 0
	s_waitcnt vmcnt(15) lgkmcnt(2)
	v_pk_add_f32 v[154:155], v[154:155], v[222:223]
	v_pk_add_f32 v[156:157], v[156:157], v[224:225]
	global_store_dwordx4 v138, v[154:157], s[46:47] sc1
	s_add_u32 s46, s46, 0x4000
	s_addc_u32 s47, s47, 0
	s_waitcnt vmcnt(15) lgkmcnt(1)
	v_pk_add_f32 v[158:159], v[158:159], v[226:227]
	v_pk_add_f32 v[160:161], v[160:161], v[228:229]
	global_store_dwordx4 v138, v[158:161], s[46:47] sc1
	s_add_u32 s46, s46, 0x4000
	s_addc_u32 s47, s47, 0
	s_waitcnt vmcnt(15) lgkmcnt(0)
	v_pk_add_f32 v[162:163], v[162:163], v[230:231]
	v_pk_add_f32 v[164:165], v[164:165], v[232:233]
	global_store_dwordx4 v138, v[162:165], s[46:47] sc1
	s_add_u32 s46, s46, 0x4000
	s_addc_u32 s47, s47, 0
	global_load_dwordx4 v[130:133], v138, s[44:45]
	s_add_u32 s44, s44, 0x4000
	s_addc_u32 s45, s45, 0
	global_load_dwordx4 v[134:137], v138, s[44:45]
	s_add_u32 s44, s44, 0x4000
	s_addc_u32 s45, s45, 0
	global_load_dwordx4 v[142:145], v138, s[44:45]
	s_add_u32 s44, s44, 0x4000
	s_addc_u32 s45, s45, 0
	global_load_dwordx4 v[146:149], v138, s[44:45]
	s_add_u32 s44, s44, 0x4000
	s_addc_u32 s45, s45, 0
	global_load_dwordx4 v[150:153], v138, s[44:45]
	s_add_u32 s44, s44, 0x4000
	s_addc_u32 s45, s45, 0
	global_load_dwordx4 v[154:157], v138, s[44:45]
	s_add_u32 s44, s44, 0x4000
	s_addc_u32 s45, s45, 0
	global_load_dwordx4 v[158:161], v138, s[44:45]
	s_add_u32 s44, s44, 0x4000
	s_addc_u32 s45, s45, 0
	global_load_dwordx4 v[162:165], v138, s[44:45]
	s_add_u32 s44, s44, 0x4000
	s_addc_u32 s45, s45, 0
	ds_read_b128 v[202:205], v141 offset:8704
	ds_read_b128 v[206:209], v141 offset:9792
	ds_read_b128 v[210:213], v141 offset:10880
	ds_read_b128 v[214:217], v141 offset:11968
	ds_read_b128 v[218:221], v141 offset:13056
	ds_read_b128 v[222:225], v141 offset:14144
	ds_read_b128 v[226:229], v141 offset:15232
	ds_read_b128 v[230:233], v141 offset:16320
	s_waitcnt vmcnt(15) lgkmcnt(7)
	v_pk_add_f32 v[166:167], v[166:167], v[202:203]
	v_pk_add_f32 v[168:169], v[168:169], v[204:205]
	global_store_dwordx4 v138, v[166:169], s[46:47] sc1
	s_add_u32 s46, s46, 0x4000
	s_addc_u32 s47, s47, 0
	s_waitcnt vmcnt(15) lgkmcnt(6)
	v_pk_add_f32 v[170:171], v[170:171], v[206:207]
	v_pk_add_f32 v[172:173], v[172:173], v[208:209]
	global_store_dwordx4 v138, v[170:173], s[46:47] sc1
	s_add_u32 s46, s46, 0x4000
	s_addc_u32 s47, s47, 0
	s_waitcnt vmcnt(15) lgkmcnt(5)
	v_pk_add_f32 v[174:175], v[174:175], v[210:211]
	v_pk_add_f32 v[176:177], v[176:177], v[212:213]
	global_store_dwordx4 v138, v[174:177], s[46:47] sc1
	s_add_u32 s46, s46, 0x4000
	s_addc_u32 s47, s47, 0
	s_waitcnt vmcnt(15) lgkmcnt(4)
	v_pk_add_f32 v[182:183], v[182:183], v[214:215]
	v_pk_add_f32 v[184:185], v[184:185], v[216:217]
	global_store_dwordx4 v138, v[182:185], s[46:47] sc1
	s_add_u32 s46, s46, 0x4000
	s_addc_u32 s47, s47, 0
	s_waitcnt vmcnt(15) lgkmcnt(3)
	v_pk_add_f32 v[186:187], v[186:187], v[218:219]
	v_pk_add_f32 v[188:189], v[188:189], v[220:221]
	global_store_dwordx4 v138, v[186:189], s[46:47] sc1
	s_add_u32 s46, s46, 0x4000
	s_addc_u32 s47, s47, 0
	s_waitcnt vmcnt(15) lgkmcnt(2)
	v_pk_add_f32 v[190:191], v[190:191], v[222:223]
	v_pk_add_f32 v[192:193], v[192:193], v[224:225]
	global_store_dwordx4 v138, v[190:193], s[46:47] sc1
	s_add_u32 s46, s46, 0x4000
	s_addc_u32 s47, s47, 0
	s_waitcnt vmcnt(15) lgkmcnt(1)
	v_pk_add_f32 v[194:195], v[194:195], v[226:227]
	v_pk_add_f32 v[196:197], v[196:197], v[228:229]
	global_store_dwordx4 v138, v[194:197], s[46:47] sc1
	s_add_u32 s46, s46, 0x4000
	s_addc_u32 s47, s47, 0
	s_waitcnt vmcnt(15) lgkmcnt(0)
	v_pk_add_f32 v[198:199], v[198:199], v[230:231]
	v_pk_add_f32 v[200:201], v[200:201], v[232:233]
	global_store_dwordx4 v138, v[198:201], s[46:47] sc1
	s_add_u32 s46, s46, 0x4000
	s_addc_u32 s47, s47, 0
	s_waitcnt lgkmcnt(0)
	global_load_dwordx4 v[166:169], v138, s[44:45]
	s_add_u32 s44, s44, 0x4000
	s_addc_u32 s45, s45, 0
	global_load_dwordx4 v[170:173], v138, s[44:45]
	s_add_u32 s44, s44, 0x4000
	s_addc_u32 s45, s45, 0
	global_load_dwordx4 v[174:177], v138, s[44:45]
	s_add_u32 s44, s44, 0x4000
	s_addc_u32 s45, s45, 0
	global_load_dwordx4 v[182:185], v138, s[44:45]
	s_add_u32 s44, s44, 0x4000
	s_addc_u32 s45, s45, 0
	global_load_dwordx4 v[186:189], v138, s[44:45]
	s_add_u32 s44, s44, 0x4000
	s_addc_u32 s45, s45, 0
	global_load_dwordx4 v[190:193], v138, s[44:45]
	s_add_u32 s44, s44, 0x4000
	s_addc_u32 s45, s45, 0
	global_load_dwordx4 v[194:197], v138, s[44:45]
	s_add_u32 s44, s44, 0x4000
	s_addc_u32 s45, s45, 0
	global_load_dwordx4 v[198:201], v138, s[44:45]
	s_add_u32 s44, s44, 0x4000
	s_addc_u32 s45, s45, 0
	ds_write_b32 v139, v60
	ds_write_b32 v139, v61 offset:272
	ds_write_b32 v139, v62 offset:544
	ds_write_b32 v139, v63 offset:816
	ds_write_b32 v139, v56 offset:64
	ds_write_b32 v139, v57 offset:336
	ds_write_b32 v139, v58 offset:608
	ds_write_b32 v139, v59 offset:880
	ds_write_b32 v139, v52 offset:128
	ds_write_b32 v139, v53 offset:400
	ds_write_b32 v139, v54 offset:672
	ds_write_b32 v139, v55 offset:944
	ds_write_b32 v139, v48 offset:192
	ds_write_b32 v139, v49 offset:464
	ds_write_b32 v139, v50 offset:736
	ds_write_b32 v139, v51 offset:1008
	ds_write_b32 v139, v44 offset:4352
	ds_write_b32 v139, v45 offset:4624
	ds_write_b32 v139, v46 offset:4896
	ds_write_b32 v139, v47 offset:5168
	ds_write_b32 v139, v32 offset:4416
	ds_write_b32 v139, v33 offset:4688
	ds_write_b32 v139, v34 offset:4960
	ds_write_b32 v139, v35 offset:5232
	ds_write_b32 v139, v28 offset:4480
	ds_write_b32 v139, v29 offset:4752
	ds_write_b32 v139, v30 offset:5024
	ds_write_b32 v139, v31 offset:5296
	ds_write_b32 v139, v24 offset:4544
	ds_write_b32 v139, v25 offset:4816
	ds_write_b32 v139, v26 offset:5088
	ds_write_b32 v139, v27 offset:5360
	ds_write_b32 v139, v20 offset:8704
	ds_write_b32 v139, v21 offset:8976
	ds_write_b32 v139, v22 offset:9248
	ds_write_b32 v139, v23 offset:9520
	ds_write_b32 v139, v16 offset:8768
	ds_write_b32 v139, v17 offset:9040
	ds_write_b32 v139, v18 offset:9312
	ds_write_b32 v139, v19 offset:9584
	ds_write_b32 v139, v12 offset:8832
	ds_write_b32 v139, v13 offset:9104
	ds_write_b32 v139, v14 offset:9376
	ds_write_b32 v139, v15 offset:9648
	ds_write_b32 v139, v8 offset:8896
	ds_write_b32 v139, v9 offset:9168
	ds_write_b32 v139, v10 offset:9440
	ds_write_b32 v139, v11 offset:9712
	ds_write_b32 v139, v4 offset:13056
	ds_write_b32 v139, v5 offset:13328
	ds_write_b32 v139, v6 offset:13600
	ds_write_b32 v139, v7 offset:13872
	ds_write_b32 v139, v0 offset:13120
	ds_write_b32 v139, v1 offset:13392
	ds_write_b32 v139, v2 offset:13664
	ds_write_b32 v139, v3 offset:13936
	ds_write_b32 v139, v40 offset:13184
	ds_write_b32 v139, v41 offset:13456
	ds_write_b32 v139, v42 offset:13728
	ds_write_b32 v139, v43 offset:14000
	ds_write_b32 v139, v36 offset:13248
	ds_write_b32 v139, v37 offset:13520
	ds_write_b32 v139, v38 offset:13792
	ds_write_b32 v139, v39 offset:14064
	s_waitcnt lgkmcnt(0)
	ds_read_b128 v[202:205], v141
	ds_read_b128 v[206:209], v141 offset:1088
	ds_read_b128 v[210:213], v141 offset:2176
	ds_read_b128 v[214:217], v141 offset:3264
	ds_read_b128 v[218:221], v141 offset:4352
	ds_read_b128 v[222:225], v141 offset:5440
	ds_read_b128 v[226:229], v141 offset:6528
	ds_read_b128 v[230:233], v141 offset:7616
	s_waitcnt vmcnt(15) lgkmcnt(7)
	v_pk_add_f32 v[130:131], v[130:131], v[202:203]
	v_pk_add_f32 v[132:133], v[132:133], v[204:205]
	global_store_dwordx4 v138, v[130:133], s[46:47] sc1
	s_add_u32 s46, s46, 0x4000
	s_addc_u32 s47, s47, 0
	s_waitcnt vmcnt(15) lgkmcnt(6)
	v_pk_add_f32 v[134:135], v[134:135], v[206:207]
	v_pk_add_f32 v[136:137], v[136:137], v[208:209]
	global_store_dwordx4 v138, v[134:137], s[46:47] sc1
	s_add_u32 s46, s46, 0x4000
	s_addc_u32 s47, s47, 0
	s_waitcnt vmcnt(15) lgkmcnt(5)
	v_pk_add_f32 v[142:143], v[142:143], v[210:211]
	v_pk_add_f32 v[144:145], v[144:145], v[212:213]
	global_store_dwordx4 v138, v[142:145], s[46:47] sc1
	s_add_u32 s46, s46, 0x4000
	s_addc_u32 s47, s47, 0
	s_waitcnt vmcnt(15) lgkmcnt(4)
	v_pk_add_f32 v[146:147], v[146:147], v[214:215]
	v_pk_add_f32 v[148:149], v[148:149], v[216:217]
	global_store_dwordx4 v138, v[146:149], s[46:47] sc1
	s_add_u32 s46, s46, 0x4000
	s_addc_u32 s47, s47, 0
	s_waitcnt vmcnt(15) lgkmcnt(3)
	v_pk_add_f32 v[150:151], v[150:151], v[218:219]
	v_pk_add_f32 v[152:153], v[152:153], v[220:221]
	global_store_dwordx4 v138, v[150:153], s[46:47] sc1
	s_add_u32 s46, s46, 0x4000
	s_addc_u32 s47, s47, 0
	s_waitcnt vmcnt(15) lgkmcnt(2)
	v_pk_add_f32 v[154:155], v[154:155], v[222:223]
	v_pk_add_f32 v[156:157], v[156:157], v[224:225]
	global_store_dwordx4 v138, v[154:157], s[46:47] sc1
	s_add_u32 s46, s46, 0x4000
	s_addc_u32 s47, s47, 0
	s_waitcnt vmcnt(15) lgkmcnt(1)
	v_pk_add_f32 v[158:159], v[158:159], v[226:227]
	v_pk_add_f32 v[160:161], v[160:161], v[228:229]
	global_store_dwordx4 v138, v[158:161], s[46:47] sc1
	s_add_u32 s46, s46, 0x4000
	s_addc_u32 s47, s47, 0
	s_waitcnt vmcnt(15) lgkmcnt(0)
	v_pk_add_f32 v[162:163], v[162:163], v[230:231]
	v_pk_add_f32 v[164:165], v[164:165], v[232:233]
	global_store_dwordx4 v138, v[162:165], s[46:47] sc1
	s_add_u32 s46, s46, 0x4000
	s_addc_u32 s47, s47, 0
	ds_read_b128 v[202:205], v141 offset:8704
	ds_read_b128 v[206:209], v141 offset:9792
	ds_read_b128 v[210:213], v141 offset:10880
	ds_read_b128 v[214:217], v141 offset:11968
	ds_read_b128 v[218:221], v141 offset:13056
	ds_read_b128 v[222:225], v141 offset:14144
	ds_read_b128 v[226:229], v141 offset:15232
	ds_read_b128 v[230:233], v141 offset:16320
	s_waitcnt vmcnt(7) lgkmcnt(7)
	v_pk_add_f32 v[166:167], v[166:167], v[202:203]
	v_pk_add_f32 v[168:169], v[168:169], v[204:205]
	global_store_dwordx4 v138, v[166:169], s[46:47] sc1
	s_add_u32 s46, s46, 0x4000
	s_addc_u32 s47, s47, 0
	s_waitcnt vmcnt(7) lgkmcnt(6)
	v_pk_add_f32 v[170:171], v[170:171], v[206:207]
	v_pk_add_f32 v[172:173], v[172:173], v[208:209]
	global_store_dwordx4 v138, v[170:173], s[46:47] sc1
	s_add_u32 s46, s46, 0x4000
	s_addc_u32 s47, s47, 0
	s_waitcnt vmcnt(7) lgkmcnt(5)
	v_pk_add_f32 v[174:175], v[174:175], v[210:211]
	v_pk_add_f32 v[176:177], v[176:177], v[212:213]
	global_store_dwordx4 v138, v[174:177], s[46:47] sc1
	s_add_u32 s46, s46, 0x4000
	s_addc_u32 s47, s47, 0
	s_waitcnt vmcnt(7) lgkmcnt(4)
	v_pk_add_f32 v[182:183], v[182:183], v[214:215]
	v_pk_add_f32 v[184:185], v[184:185], v[216:217]
	global_store_dwordx4 v138, v[182:185], s[46:47] sc1
	s_add_u32 s46, s46, 0x4000
	s_addc_u32 s47, s47, 0
	s_waitcnt vmcnt(7) lgkmcnt(3)
	v_pk_add_f32 v[186:187], v[186:187], v[218:219]
	v_pk_add_f32 v[188:189], v[188:189], v[220:221]
	global_store_dwordx4 v138, v[186:189], s[46:47] sc1
	s_add_u32 s46, s46, 0x4000
	s_addc_u32 s47, s47, 0
	s_waitcnt vmcnt(7) lgkmcnt(2)
	v_pk_add_f32 v[190:191], v[190:191], v[222:223]
	v_pk_add_f32 v[192:193], v[192:193], v[224:225]
	global_store_dwordx4 v138, v[190:193], s[46:47] sc1
	s_add_u32 s46, s46, 0x4000
	s_addc_u32 s47, s47, 0
	s_waitcnt vmcnt(7) lgkmcnt(1)
	v_pk_add_f32 v[194:195], v[194:195], v[226:227]
	v_pk_add_f32 v[196:197], v[196:197], v[228:229]
	global_store_dwordx4 v138, v[194:197], s[46:47] sc1
	s_add_u32 s46, s46, 0x4000
	s_addc_u32 s47, s47, 0
	s_waitcnt vmcnt(7) lgkmcnt(0)
	v_pk_add_f32 v[198:199], v[198:199], v[230:231]
	v_pk_add_f32 v[200:201], v[200:201], v[232:233]
	global_store_dwordx4 v138, v[198:201], s[46:47] sc1
	s_add_u32 s46, s46, 0x4000
	s_addc_u32 s47, s47, 0
	s_cmpk_lt_i32 s58, 0x100
	s_cbranch_scc0 .LBB0_1337

.LBB0_1635:
	s_add_i32 s44, s44, s82
	s_add_i32 s43, s43, s82
	v_and_b32_e32 v178, 15, v181
	v_bfe_u32 v138, v181, 4, 2
	v_lshlrev_b32_e32 v141, 4, v178
	s_movk_i32 s20, 0x110
	v_mad_u32_u24 v141, v138, s20, v141
	v_lshlrev_b32_e32 v139, 2, v178
	s_movk_i32 s20, 0x440
	v_mad_u32_u24 v139, v138, s20, v139
	v_lshlrev_b32_e32 v138, 12, v138
	v_lshl_add_u32 v138, v178, 4, v138
	v_lshrrev_b32_e32 v178, 6, v181
	v_mul_u32_u24_e32 v178, 0x4400, v178
	v_add_u32_e32 v141, v141, v178
	v_add_u32_e32 v139, v139, v178
	v_bfe_u32 v178, v181, 6, 2
	v_lshl_add_u32 v138, v178, 8, v138
	v_lshrrev_b32_e32 v178, 8, v181
	v_lshl_add_u32 v138, v178, 19, v138
	s_lshl_b32 s20, s30, 20
	v_add_u32_e32 v138, s20, v138
	s_lshl_b32 s20, s4, 10
	v_add_u32_e32 v138, s20, v138
	s_mov_b32 s36, s78
	s_mov_b32 s37, s79
	s_mov_b32 s38, s78
	s_mov_b32 s39, s79
	global_load_dwordx4 v[130:133], v138, s[36:37]
	s_add_u32 s36, s36, 0x4000
	s_addc_u32 s37, s37, 0
	global_load_dwordx4 v[134:137], v138, s[36:37]
	s_add_u32 s36, s36, 0x4000
	s_addc_u32 s37, s37, 0
	global_load_dwordx4 v[142:145], v138, s[36:37]
	s_add_u32 s36, s36, 0x4000
	s_addc_u32 s37, s37, 0
	global_load_dwordx4 v[146:149], v138, s[36:37]
	s_add_u32 s36, s36, 0x4000
	s_addc_u32 s37, s37, 0
	global_load_dwordx4 v[150:153], v138, s[36:37]
	s_add_u32 s36, s36, 0x4000
	s_addc_u32 s37, s37, 0
	global_load_dwordx4 v[154:157], v138, s[36:37]
	s_add_u32 s36, s36, 0x4000
	s_addc_u32 s37, s37, 0
	global_load_dwordx4 v[158:161], v138, s[36:37]
	s_add_u32 s36, s36, 0x4000
	s_addc_u32 s37, s37, 0
	global_load_dwordx4 v[162:165], v138, s[36:37]
	s_add_u32 s36, s36, 0x4000
	s_addc_u32 s37, s37, 0
	global_load_dwordx4 v[166:169], v138, s[36:37]
	s_add_u32 s36, s36, 0x4000
	s_addc_u32 s37, s37, 0
	global_load_dwordx4 v[170:173], v138, s[36:37]
	s_add_u32 s36, s36, 0x4000
	s_addc_u32 s37, s37, 0
	global_load_dwordx4 v[174:177], v138, s[36:37]
	s_add_u32 s36, s36, 0x4000
	s_addc_u32 s37, s37, 0
	global_load_dwordx4 v[182:185], v138, s[36:37]
	s_add_u32 s36, s36, 0x4000
	s_addc_u32 s37, s37, 0
	global_load_dwordx4 v[186:189], v138, s[36:37]
	s_add_u32 s36, s36, 0x4000
	s_addc_u32 s37, s37, 0
	global_load_dwordx4 v[190:193], v138, s[36:37]
	s_add_u32 s36, s36, 0x4000
	s_addc_u32 s37, s37, 0
	global_load_dwordx4 v[194:197], v138, s[36:37]
	s_add_u32 s36, s36, 0x4000
	s_addc_u32 s37, s37, 0
	global_load_dwordx4 v[198:201], v138, s[36:37]
	s_add_u32 s36, s36, 0x4000
	s_addc_u32 s37, s37, 0
	ds_write_b32 v139, v124
	ds_write_b32 v139, v125 offset:272
	ds_write_b32 v139, v126 offset:544
	ds_write_b32 v139, v127 offset:816
	ds_write_b32 v139, v120 offset:64
	ds_write_b32 v139, v121 offset:336
	ds_write_b32 v139, v122 offset:608
	ds_write_b32 v139, v123 offset:880
	ds_write_b32 v139, v116 offset:128
	ds_write_b32 v139, v117 offset:400
	ds_write_b32 v139, v118 offset:672
	ds_write_b32 v139, v119 offset:944
	ds_write_b32 v139, v112 offset:192
	ds_write_b32 v139, v113 offset:464
	ds_write_b32 v139, v114 offset:736
	ds_write_b32 v139, v115 offset:1008
	ds_write_b32 v139, v108 offset:4352
	ds_write_b32 v139, v109 offset:4624
	ds_write_b32 v139, v110 offset:4896
	ds_write_b32 v139, v111 offset:5168
	ds_write_b32 v139, v104 offset:4416
	ds_write_b32 v139, v105 offset:4688
	ds_write_b32 v139, v106 offset:4960
	ds_write_b32 v139, v107 offset:5232
	ds_write_b32 v139, v100 offset:4480
	ds_write_b32 v139, v101 offset:4752
	ds_write_b32 v139, v102 offset:5024
	ds_write_b32 v139, v103 offset:5296
	ds_write_b32 v139, v96 offset:4544
	ds_write_b32 v139, v97 offset:4816
	ds_write_b32 v139, v98 offset:5088
	ds_write_b32 v139, v99 offset:5360
	ds_write_b32 v139, v92 offset:8704
	ds_write_b32 v139, v93 offset:8976
	ds_write_b32 v139, v94 offset:9248
	ds_write_b32 v139, v95 offset:9520
	ds_write_b32 v139, v88 offset:8768
	ds_write_b32 v139, v89 offset:9040
	ds_write_b32 v139, v90 offset:9312
	ds_write_b32 v139, v91 offset:9584
	ds_write_b32 v139, v84 offset:8832
	ds_write_b32 v139, v85 offset:9104
	ds_write_b32 v139, v86 offset:9376
	ds_write_b32 v139, v87 offset:9648
	ds_write_b32 v139, v80 offset:8896
	ds_write_b32 v139, v81 offset:9168
	ds_write_b32 v139, v82 offset:9440
	ds_write_b32 v139, v83 offset:9712
	ds_write_b32 v139, v76 offset:13056
	ds_write_b32 v139, v77 offset:13328
	ds_write_b32 v139, v78 offset:13600
	ds_write_b32 v139, v79 offset:13872
	ds_write_b32 v139, v72 offset:13120
	ds_write_b32 v139, v73 offset:13392
	ds_write_b32 v139, v74 offset:13664
	ds_write_b32 v139, v75 offset:13936
	ds_write_b32 v139, v68 offset:13184
	ds_write_b32 v139, v69 offset:13456
	ds_write_b32 v139, v70 offset:13728
	ds_write_b32 v139, v71 offset:14000
	ds_write_b32 v139, v64 offset:13248
	ds_write_b32 v139, v65 offset:13520
	ds_write_b32 v139, v66 offset:13792
	ds_write_b32 v139, v67 offset:14064
	s_waitcnt lgkmcnt(0)
	ds_read_b128 v[202:205], v141
	ds_read_b128 v[206:209], v141 offset:1088
	ds_read_b128 v[210:213], v141 offset:2176
	ds_read_b128 v[214:217], v141 offset:3264
	ds_read_b128 v[218:221], v141 offset:4352
	ds_read_b128 v[222:225], v141 offset:5440
	ds_read_b128 v[226:229], v141 offset:6528
	ds_read_b128 v[230:233], v141 offset:7616
	s_waitcnt vmcnt(15) lgkmcnt(7)
	v_pk_add_f32 v[130:131], v[130:131], v[202:203]
	v_pk_add_f32 v[132:133], v[132:133], v[204:205]
	global_store_dwordx4 v138, v[130:133], s[38:39] sc1
	s_add_u32 s38, s38, 0x4000
	s_addc_u32 s39, s39, 0
	s_waitcnt vmcnt(15) lgkmcnt(6)
	v_pk_add_f32 v[134:135], v[134:135], v[206:207]
	v_pk_add_f32 v[136:137], v[136:137], v[208:209]
	global_store_dwordx4 v138, v[134:137], s[38:39] sc1
	s_add_u32 s38, s38, 0x4000
	s_addc_u32 s39, s39, 0
	s_waitcnt vmcnt(15) lgkmcnt(5)
	v_pk_add_f32 v[142:143], v[142:143], v[210:211]
	v_pk_add_f32 v[144:145], v[144:145], v[212:213]
	global_store_dwordx4 v138, v[142:145], s[38:39] sc1
	s_add_u32 s38, s38, 0x4000
	s_addc_u32 s39, s39, 0
	s_waitcnt vmcnt(15) lgkmcnt(4)
	v_pk_add_f32 v[146:147], v[146:147], v[214:215]
	v_pk_add_f32 v[148:149], v[148:149], v[216:217]
	global_store_dwordx4 v138, v[146:149], s[38:39] sc1
	s_add_u32 s38, s38, 0x4000
	s_addc_u32 s39, s39, 0
	s_waitcnt vmcnt(15) lgkmcnt(3)
	v_pk_add_f32 v[150:151], v[150:151], v[218:219]
	v_pk_add_f32 v[152:153], v[152:153], v[220:221]
	global_store_dwordx4 v138, v[150:153], s[38:39] sc1
	s_add_u32 s38, s38, 0x4000
	s_addc_u32 s39, s39, 0
	s_waitcnt vmcnt(15) lgkmcnt(2)
	v_pk_add_f32 v[154:155], v[154:155], v[222:223]
	v_pk_add_f32 v[156:157], v[156:157], v[224:225]
	global_store_dwordx4 v138, v[154:157], s[38:39] sc1
	s_add_u32 s38, s38, 0x4000
	s_addc_u32 s39, s39, 0
	s_waitcnt vmcnt(15) lgkmcnt(1)
	v_pk_add_f32 v[158:159], v[158:159], v[226:227]
	v_pk_add_f32 v[160:161], v[160:161], v[228:229]
	global_store_dwordx4 v138, v[158:161], s[38:39] sc1
	s_add_u32 s38, s38, 0x4000
	s_addc_u32 s39, s39, 0
	s_waitcnt vmcnt(15) lgkmcnt(0)
	v_pk_add_f32 v[162:163], v[162:163], v[230:231]
	v_pk_add_f32 v[164:165], v[164:165], v[232:233]
	global_store_dwordx4 v138, v[162:165], s[38:39] sc1
	s_add_u32 s38, s38, 0x4000
	s_addc_u32 s39, s39, 0
	global_load_dwordx4 v[130:133], v138, s[36:37]
	s_add_u32 s36, s36, 0x4000
	s_addc_u32 s37, s37, 0
	global_load_dwordx4 v[134:137], v138, s[36:37]
	s_add_u32 s36, s36, 0x4000
	s_addc_u32 s37, s37, 0
	global_load_dwordx4 v[142:145], v138, s[36:37]
	s_add_u32 s36, s36, 0x4000
	s_addc_u32 s37, s37, 0
	global_load_dwordx4 v[146:149], v138, s[36:37]
	s_add_u32 s36, s36, 0x4000
	s_addc_u32 s37, s37, 0
	global_load_dwordx4 v[150:153], v138, s[36:37]
	s_add_u32 s36, s36, 0x4000
	s_addc_u32 s37, s37, 0
	global_load_dwordx4 v[154:157], v138, s[36:37]
	s_add_u32 s36, s36, 0x4000
	s_addc_u32 s37, s37, 0
	global_load_dwordx4 v[158:161], v138, s[36:37]
	s_add_u32 s36, s36, 0x4000
	s_addc_u32 s37, s37, 0
	global_load_dwordx4 v[162:165], v138, s[36:37]
	s_add_u32 s36, s36, 0x4000
	s_addc_u32 s37, s37, 0
	ds_read_b128 v[202:205], v141 offset:8704
	ds_read_b128 v[206:209], v141 offset:9792
	ds_read_b128 v[210:213], v141 offset:10880
	ds_read_b128 v[214:217], v141 offset:11968
	ds_read_b128 v[218:221], v141 offset:13056
	ds_read_b128 v[222:225], v141 offset:14144
	ds_read_b128 v[226:229], v141 offset:15232
	ds_read_b128 v[230:233], v141 offset:16320
	s_waitcnt vmcnt(15) lgkmcnt(7)
	v_pk_add_f32 v[166:167], v[166:167], v[202:203]
	v_pk_add_f32 v[168:169], v[168:169], v[204:205]
	global_store_dwordx4 v138, v[166:169], s[38:39] sc1
	s_add_u32 s38, s38, 0x4000
	s_addc_u32 s39, s39, 0
	s_waitcnt vmcnt(15) lgkmcnt(6)
	v_pk_add_f32 v[170:171], v[170:171], v[206:207]
	v_pk_add_f32 v[172:173], v[172:173], v[208:209]
	global_store_dwordx4 v138, v[170:173], s[38:39] sc1
	s_add_u32 s38, s38, 0x4000
	s_addc_u32 s39, s39, 0
	s_waitcnt vmcnt(15) lgkmcnt(5)
	v_pk_add_f32 v[174:175], v[174:175], v[210:211]
	v_pk_add_f32 v[176:177], v[176:177], v[212:213]
	global_store_dwordx4 v138, v[174:177], s[38:39] sc1
	s_add_u32 s38, s38, 0x4000
	s_addc_u32 s39, s39, 0
	s_waitcnt vmcnt(15) lgkmcnt(4)
	v_pk_add_f32 v[182:183], v[182:183], v[214:215]
	v_pk_add_f32 v[184:185], v[184:185], v[216:217]
	global_store_dwordx4 v138, v[182:185], s[38:39] sc1
	s_add_u32 s38, s38, 0x4000
	s_addc_u32 s39, s39, 0
	s_waitcnt vmcnt(15) lgkmcnt(3)
	v_pk_add_f32 v[186:187], v[186:187], v[218:219]
	v_pk_add_f32 v[188:189], v[188:189], v[220:221]
	global_store_dwordx4 v138, v[186:189], s[38:39] sc1
	s_add_u32 s38, s38, 0x4000
	s_addc_u32 s39, s39, 0
	s_waitcnt vmcnt(15) lgkmcnt(2)
	v_pk_add_f32 v[190:191], v[190:191], v[222:223]
	v_pk_add_f32 v[192:193], v[192:193], v[224:225]
	global_store_dwordx4 v138, v[190:193], s[38:39] sc1
	s_add_u32 s38, s38, 0x4000
	s_addc_u32 s39, s39, 0
	s_waitcnt vmcnt(15) lgkmcnt(1)
	v_pk_add_f32 v[194:195], v[194:195], v[226:227]
	v_pk_add_f32 v[196:197], v[196:197], v[228:229]
	global_store_dwordx4 v138, v[194:197], s[38:39] sc1
	s_add_u32 s38, s38, 0x4000
	s_addc_u32 s39, s39, 0
	s_waitcnt vmcnt(15) lgkmcnt(0)
	v_pk_add_f32 v[198:199], v[198:199], v[230:231]
	v_pk_add_f32 v[200:201], v[200:201], v[232:233]
	global_store_dwordx4 v138, v[198:201], s[38:39] sc1
	s_add_u32 s38, s38, 0x4000
	s_addc_u32 s39, s39, 0
	s_waitcnt lgkmcnt(0)
	global_load_dwordx4 v[166:169], v138, s[36:37]
	s_add_u32 s36, s36, 0x4000
	s_addc_u32 s37, s37, 0
	global_load_dwordx4 v[170:173], v138, s[36:37]
	s_add_u32 s36, s36, 0x4000
	s_addc_u32 s37, s37, 0
	global_load_dwordx4 v[174:177], v138, s[36:37]
	s_add_u32 s36, s36, 0x4000
	s_addc_u32 s37, s37, 0
	global_load_dwordx4 v[182:185], v138, s[36:37]
	s_add_u32 s36, s36, 0x4000
	s_addc_u32 s37, s37, 0
	global_load_dwordx4 v[186:189], v138, s[36:37]
	s_add_u32 s36, s36, 0x4000
	s_addc_u32 s37, s37, 0
	global_load_dwordx4 v[190:193], v138, s[36:37]
	s_add_u32 s36, s36, 0x4000
	s_addc_u32 s37, s37, 0
	global_load_dwordx4 v[194:197], v138, s[36:37]
	s_add_u32 s36, s36, 0x4000
	s_addc_u32 s37, s37, 0
	global_load_dwordx4 v[198:201], v138, s[36:37]
	s_add_u32 s36, s36, 0x4000
	s_addc_u32 s37, s37, 0
	ds_write_b32 v139, v60
	ds_write_b32 v139, v61 offset:272
	ds_write_b32 v139, v62 offset:544
	ds_write_b32 v139, v63 offset:816
	ds_write_b32 v139, v56 offset:64
	ds_write_b32 v139, v57 offset:336
	ds_write_b32 v139, v58 offset:608
	ds_write_b32 v139, v59 offset:880
	ds_write_b32 v139, v52 offset:128
	ds_write_b32 v139, v53 offset:400
	ds_write_b32 v139, v54 offset:672
	ds_write_b32 v139, v55 offset:944
	ds_write_b32 v139, v48 offset:192
	ds_write_b32 v139, v49 offset:464
	ds_write_b32 v139, v50 offset:736
	ds_write_b32 v139, v51 offset:1008
	ds_write_b32 v139, v44 offset:4352
	ds_write_b32 v139, v45 offset:4624
	ds_write_b32 v139, v46 offset:4896
	ds_write_b32 v139, v47 offset:5168
	ds_write_b32 v139, v32 offset:4416
	ds_write_b32 v139, v33 offset:4688
	ds_write_b32 v139, v34 offset:4960
	ds_write_b32 v139, v35 offset:5232
	ds_write_b32 v139, v28 offset:4480
	ds_write_b32 v139, v29 offset:4752
	ds_write_b32 v139, v30 offset:5024
	ds_write_b32 v139, v31 offset:5296
	ds_write_b32 v139, v24 offset:4544
	ds_write_b32 v139, v25 offset:4816
	ds_write_b32 v139, v26 offset:5088
	ds_write_b32 v139, v27 offset:5360
	ds_write_b32 v139, v20 offset:8704
	ds_write_b32 v139, v21 offset:8976
	ds_write_b32 v139, v22 offset:9248
	ds_write_b32 v139, v23 offset:9520
	ds_write_b32 v139, v16 offset:8768
	ds_write_b32 v139, v17 offset:9040
	ds_write_b32 v139, v18 offset:9312
	ds_write_b32 v139, v19 offset:9584
	ds_write_b32 v139, v12 offset:8832
	ds_write_b32 v139, v13 offset:9104
	ds_write_b32 v139, v14 offset:9376
	ds_write_b32 v139, v15 offset:9648
	ds_write_b32 v139, v8 offset:8896
	ds_write_b32 v139, v9 offset:9168
	ds_write_b32 v139, v10 offset:9440
	ds_write_b32 v139, v11 offset:9712
	ds_write_b32 v139, v4 offset:13056
	ds_write_b32 v139, v5 offset:13328
	ds_write_b32 v139, v6 offset:13600
	ds_write_b32 v139, v7 offset:13872
	ds_write_b32 v139, v0 offset:13120
	ds_write_b32 v139, v1 offset:13392
	ds_write_b32 v139, v2 offset:13664
	ds_write_b32 v139, v3 offset:13936
	ds_write_b32 v139, v40 offset:13184
	ds_write_b32 v139, v41 offset:13456
	ds_write_b32 v139, v42 offset:13728
	ds_write_b32 v139, v43 offset:14000
	ds_write_b32 v139, v36 offset:13248
	ds_write_b32 v139, v37 offset:13520
	ds_write_b32 v139, v38 offset:13792
	ds_write_b32 v139, v39 offset:14064
	s_waitcnt lgkmcnt(0)
	ds_read_b128 v[202:205], v141
	ds_read_b128 v[206:209], v141 offset:1088
	ds_read_b128 v[210:213], v141 offset:2176
	ds_read_b128 v[214:217], v141 offset:3264
	ds_read_b128 v[218:221], v141 offset:4352
	ds_read_b128 v[222:225], v141 offset:5440
	ds_read_b128 v[226:229], v141 offset:6528
	ds_read_b128 v[230:233], v141 offset:7616
	s_waitcnt vmcnt(15) lgkmcnt(7)
	v_pk_add_f32 v[130:131], v[130:131], v[202:203]
	v_pk_add_f32 v[132:133], v[132:133], v[204:205]
	global_store_dwordx4 v138, v[130:133], s[38:39] sc1
	s_add_u32 s38, s38, 0x4000
	s_addc_u32 s39, s39, 0
	s_waitcnt vmcnt(15) lgkmcnt(6)
	v_pk_add_f32 v[134:135], v[134:135], v[206:207]
	v_pk_add_f32 v[136:137], v[136:137], v[208:209]
	global_store_dwordx4 v138, v[134:137], s[38:39] sc1
	s_add_u32 s38, s38, 0x4000
	s_addc_u32 s39, s39, 0
	s_waitcnt vmcnt(15) lgkmcnt(5)
	v_pk_add_f32 v[142:143], v[142:143], v[210:211]
	v_pk_add_f32 v[144:145], v[144:145], v[212:213]
	global_store_dwordx4 v138, v[142:145], s[38:39] sc1
	s_add_u32 s38, s38, 0x4000
	s_addc_u32 s39, s39, 0
	s_waitcnt vmcnt(15) lgkmcnt(4)
	v_pk_add_f32 v[146:147], v[146:147], v[214:215]
	v_pk_add_f32 v[148:149], v[148:149], v[216:217]
	global_store_dwordx4 v138, v[146:149], s[38:39] sc1
	s_add_u32 s38, s38, 0x4000
	s_addc_u32 s39, s39, 0
	s_waitcnt vmcnt(15) lgkmcnt(3)
	v_pk_add_f32 v[150:151], v[150:151], v[218:219]
	v_pk_add_f32 v[152:153], v[152:153], v[220:221]
	global_store_dwordx4 v138, v[150:153], s[38:39] sc1
	s_add_u32 s38, s38, 0x4000
	s_addc_u32 s39, s39, 0
	s_waitcnt vmcnt(15) lgkmcnt(2)
	v_pk_add_f32 v[154:155], v[154:155], v[222:223]
	v_pk_add_f32 v[156:157], v[156:157], v[224:225]
	global_store_dwordx4 v138, v[154:157], s[38:39] sc1
	s_add_u32 s38, s38, 0x4000
	s_addc_u32 s39, s39, 0
	s_waitcnt vmcnt(15) lgkmcnt(1)
	v_pk_add_f32 v[158:159], v[158:159], v[226:227]
	v_pk_add_f32 v[160:161], v[160:161], v[228:229]
	global_store_dwordx4 v138, v[158:161], s[38:39] sc1
	s_add_u32 s38, s38, 0x4000
	s_addc_u32 s39, s39, 0
	s_waitcnt vmcnt(15) lgkmcnt(0)
	v_pk_add_f32 v[162:163], v[162:163], v[230:231]
	v_pk_add_f32 v[164:165], v[164:165], v[232:233]
	global_store_dwordx4 v138, v[162:165], s[38:39] sc1
	s_add_u32 s38, s38, 0x4000
	s_addc_u32 s39, s39, 0
	ds_read_b128 v[202:205], v141 offset:8704
	ds_read_b128 v[206:209], v141 offset:9792
	ds_read_b128 v[210:213], v141 offset:10880
	ds_read_b128 v[214:217], v141 offset:11968
	ds_read_b128 v[218:221], v141 offset:13056
	ds_read_b128 v[222:225], v141 offset:14144
	ds_read_b128 v[226:229], v141 offset:15232
	ds_read_b128 v[230:233], v141 offset:16320
	s_waitcnt vmcnt(7) lgkmcnt(7)
	v_pk_add_f32 v[166:167], v[166:167], v[202:203]
	v_pk_add_f32 v[168:169], v[168:169], v[204:205]
	global_store_dwordx4 v138, v[166:169], s[38:39] sc1
	s_add_u32 s38, s38, 0x4000
	s_addc_u32 s39, s39, 0
	s_waitcnt vmcnt(7) lgkmcnt(6)
	v_pk_add_f32 v[170:171], v[170:171], v[206:207]
	v_pk_add_f32 v[172:173], v[172:173], v[208:209]
	global_store_dwordx4 v138, v[170:173], s[38:39] sc1
	s_add_u32 s38, s38, 0x4000
	s_addc_u32 s39, s39, 0
	s_waitcnt vmcnt(7) lgkmcnt(5)
	v_pk_add_f32 v[174:175], v[174:175], v[210:211]
	v_pk_add_f32 v[176:177], v[176:177], v[212:213]
	global_store_dwordx4 v138, v[174:177], s[38:39] sc1
	s_add_u32 s38, s38, 0x4000
	s_addc_u32 s39, s39, 0
	s_waitcnt vmcnt(7) lgkmcnt(4)
	v_pk_add_f32 v[182:183], v[182:183], v[214:215]
	v_pk_add_f32 v[184:185], v[184:185], v[216:217]
	global_store_dwordx4 v138, v[182:185], s[38:39] sc1
	s_add_u32 s38, s38, 0x4000
	s_addc_u32 s39, s39, 0
	s_waitcnt vmcnt(7) lgkmcnt(3)
	v_pk_add_f32 v[186:187], v[186:187], v[218:219]
	v_pk_add_f32 v[188:189], v[188:189], v[220:221]
	global_store_dwordx4 v138, v[186:189], s[38:39] sc1
	s_add_u32 s38, s38, 0x4000
	s_addc_u32 s39, s39, 0
	s_waitcnt vmcnt(7) lgkmcnt(2)
	v_pk_add_f32 v[190:191], v[190:191], v[222:223]
	v_pk_add_f32 v[192:193], v[192:193], v[224:225]
	global_store_dwordx4 v138, v[190:193], s[38:39] sc1
	s_add_u32 s38, s38, 0x4000
	s_addc_u32 s39, s39, 0
	s_waitcnt vmcnt(7) lgkmcnt(1)
	v_pk_add_f32 v[194:195], v[194:195], v[226:227]
	v_pk_add_f32 v[196:197], v[196:197], v[228:229]
	global_store_dwordx4 v138, v[194:197], s[38:39] sc1
	s_add_u32 s38, s38, 0x4000
	s_addc_u32 s39, s39, 0
	s_waitcnt vmcnt(7) lgkmcnt(0)
	v_pk_add_f32 v[198:199], v[198:199], v[230:231]
	v_pk_add_f32 v[200:201], v[200:201], v[232:233]
	global_store_dwordx4 v138, v[198:201], s[38:39] sc1
	s_add_u32 s38, s38, 0x4000
	s_addc_u32 s39, s39, 0
	s_cmpk_lt_i32 s44, 0x100
	s_cbranch_scc0 .LBB0_1642
